# QKV and QABS epilogues in four 16-row passes through stage-1 LDS areas; the next tile's first K-tile is LDS-DMA staged into the stage-0 areas during the epilogue (tile prologue skips that load)
# baseline (speedup 1.0000x reference)
; DI float shx(float v, int mask, int lane) { return __int_as_float(__builtin_amdgcn_ds_bpermute((lane ^ mask) << 2, __float_as_int(v))); }
; DI void epi_slab(const GemmCfg c, const f32x16 (&acc)[4], float* sW, const float* rss, const size_t row0, const int g, const int lane,
;                  float* const g_h, u16* const g_hb, float* const g_out, const int final_out) {
;     ...
;       const float rs = c.use_rs ? rsqrtf(rss[r] * invK + 1e-6f) : 1.f;
;       if (c.epi == EPI_QKV) {
;         f32x4 x = v * rs;
;         float s = x[0] * x[0] + x[1] * x[1] + x[2] * x[2] + x[3] * x[3];
;         s += shx(s, 1, ln_); s += shx(s, 2, ln_); s += shx(s, 4, ln_); s += shx(s, 8, ln_);
;         if (g < c.nk_end) {
;           const float r2 = rsqrtf(s * (1.f / 64.f) + 1e-6f) * (g < 8 ? 0.125f * LOG2E : 1.f);
;           f32x4 gn = *(const f32x4*)(c.gain + (g < 8 ? 0 : 64) + (c4 & 63));
;           x = x * gn * r2;
;         }
;         *(u32x2*)(c.o16 + row * c.ldo + col) = MK2(pack2(x[0], x[1]), pack2(x[2], x[3]));
; DI void gemm_run(const GemmCfg c, char* smem, float* const g_h, u16* const g_hb, float* const g_out, const int final_out) {
;     ...
;   for (int slot = Lb; slot < ntiles; slot += G) {
;     const int sr = slot / srow, idx = slot - sr * srow;
;     const int tm = sr < 8 ? sr * 8 + (idx & 7) : 64;
;     const int tn = sr < 8 ? (idx >> 3) : idx;
;     const u16* Ag = c.A + (size_t)(tm * 256 + lrow) * c.lda + tn * c.a_koff_tn + lch * 8;
;     const u16* Bg = c.Bt + (size_t)(tn * 256 + lrow) * K + lch * 8;
;     const size_t astep = (size_t)64 * c.lda, bstep = (size_t)64 * K;
.Lqkv2:
	v_and_b32_e32 v222, 15, v185
	v_lshrrev_b32_e32 v223, 4, v185
	s_lshl_b32 s4, s86, 2
	s_add_i32 s4, s4, 0x24000
	v_lshl_add_u32 v224, v223, 4, s4
	ds_read_b128 v[226:229], v224
	ds_read_b128 v[230:233], v224 offset:64
	ds_read_b128 v[234:237], v224 offset:128
	ds_read_b128 v[238:241], v224 offset:192
	v_mov_b32_e32 v148, v130
	v_lshlrev_b32_e32 v206, 2, v222
	global_load_dword v140, v206, s[58:59]
	global_load_dword v142, v206, s[58:59] offset:64
	global_load_dword v144, v206, s[58:59] offset:128
	global_load_dword v146, v206, s[58:59] offset:192
	s_lshr_b32 s4, s86, 5
	s_or_b32 s4, s4, s75
	s_and_b32 s5, s4, 3
	s_mul_i32 s5, s5, 0x2400
	s_cmp_lt_u32 s4, 4
	s_mov_b32 s4, 0x1b000
	s_cselect_b32 s4, 0x9000, s4
	s_add_i32 s4, s4, s5
	v_mul_u32_u24_e32 v198, 0x840, v223
	v_lshl_add_u32 v198, v222, 2, v198
	v_add_u32_e32 v198, s4, v198
	v_add_u32_e32 v199, 0x420, v198
	v_lshrrev_b32_e32 v202, 5, v185
	v_and_b32_e32 v206, 31, v185
	v_mul_u32_u24_e32 v204, 0x210, v202
	v_lshl_add_u32 v204, v206, 4, v204
	v_add_u32_e32 v250, s4, v204
	v_add_u32_e32 v204, s6, v202
	v_mul_lo_u32 v204, v204, s92
	v_lshl_add_u32 v206, v206, 2, s64
	v_lshl_add_u32 v204, v206, 1, v204
	v_mov_b32_e32 v205, 0
	v_lshl_add_u64 v[204:205], v[204:205], 0, s[56:57]
	v_mov_b32_e32 v202, v250
	v_mov_b32_e32 v250, 0x3c800000
	v_readlane_b32 s6, v254, 26
	s_mov_b32 s9, 0
	s_nop 0
	s_add_i32 s7, s48, s6
	s_cmp_ge_i32 s7, s74
	s_cbranch_scc1 .Lqkv2_nopf
	s_abs_i32 s1, s7
	s_mul_hi_u32 s4, s1, s69
	s_mul_i32 s5, s4, s30
	s_ashr_i32 s0, s7, 31
	s_sub_i32 s1, s1, s5
	s_xor_b32 s0, s0, s63
	s_add_i32 s5, s4, 1
	s_sub_i32 s6, s1, s30
	s_cmp_ge_u32 s1, s30
	s_cselect_b32 s4, s5, s4
	s_cselect_b32 s1, s6, s1
	s_add_i32 s5, s4, 1
	s_cmp_ge_u32 s1, s30
	s_cselect_b32 s1, s5, s4
	s_xor_b32 s1, s1, s0
	s_sub_i32 s0, s1, s0
	s_mul_i32 s1, s0, s65
	s_sub_i32 s1, s7, s1
	s_lshl_b32 s4, s0, 3
	s_and_b32 s5, s7, 7
	s_or_b32 s4, s4, s5
	s_ashr_i32 s5, s1, 3
	s_cmp_lt_i32 s0, 8
	s_cselect_b32 s78, s4, 64
	s_cselect_b32 s49, s5, s1
	v_lshrrev_b32_e32 v128, 3, v185
	v_and_b32_e32 v129, 7, v185
	v_xor_b32_e32 v129, v129, v128
	v_lshlrev_b32_e32 v129, 4, v129
	s_lshl_b32 s0, s62, 1
	v_mul_lo_u32 v130, v128, s0
	s_lshl_b32 s1, s62, 4
	v_add_u32_e32 v130, v130, v129
	v_add_u32_e32 v131, s1, v130
	v_add_u32_e32 v132, s1, v131
	v_add_u32_e32 v133, s1, v132
	s_lshl_b32 s0, s60, 1
	v_mul_lo_u32 v134, v128, s0
	s_lshl_b32 s1, s60, 4
	v_add_u32_e32 v134, v134, v129
	v_add_u32_e32 v135, s1, v134
	v_add_u32_e32 v136, s1, v135
	v_add_u32_e32 v137, s1, v136
	s_lshl_b32 s8, s75, 5
	s_add_i32 s8, s8, s86
	s_lshl_b32 s0, s78, 8
	s_add_i32 s0, s0, s8
	s_mul_i32 s0, s0, s62
	s_mul_i32 s1, s49, s2
	s_add_i32 s0, s0, s1
	s_lshl_b32 s0, s0, 1
	s_add_u32 s4, s54, s0
	s_addc_u32 s5, s55, 0
	v_readlane_b32 s6, v255, 5
	v_readlane_b32 s7, v255, 6
	s_lshl_b32 s0, s49, 8
	s_add_i32 s0, s0, s8
	s_mul_i32 s0, s0, s60
	s_lshl_b32 s0, s0, 1
	s_add_u32 s6, s6, s0
	s_addc_u32 s7, s7, 0
	s_lshl_b32 s8, s8, 7
	s_add_u32 m0, s8, 0x0
	s_nop 0
	global_load_lds_dwordx4 v130, s[4:5]
	s_add_u32 m0, s8, 0x12000
	s_nop 0
	global_load_lds_dwordx4 v134, s[6:7]
	s_add_u32 m0, s8, 0x400
	s_nop 0
	global_load_lds_dwordx4 v131, s[4:5]
	s_add_u32 m0, s8, 0x12400
	s_nop 0
	global_load_lds_dwordx4 v135, s[6:7]
	s_add_u32 m0, s8, 0x800
	s_nop 0
	global_load_lds_dwordx4 v132, s[4:5]
	s_add_u32 m0, s8, 0x12800
	s_nop 0
	global_load_lds_dwordx4 v136, s[6:7]
	s_add_u32 m0, s8, 0xc00
	s_nop 0
	global_load_lds_dwordx4 v133, s[4:5]
	s_add_u32 m0, s8, 0x12c00
	s_nop 0
	global_load_lds_dwordx4 v137, s[6:7]
	s_mov_b32 s9, 1
	s_waitcnt vmcnt(8)
	s_branch .Lqkv2_pfd

; DI float shx(float v, int mask, int lane) { return __int_as_float(__builtin_amdgcn_ds_bpermute((lane ^ mask) << 2, __float_as_int(v))); }
; DI void epi_slab(const GemmCfg c, const f32x16 (&acc)[4], float* sW, const float* rss, const size_t row0, const int g, const int lane,
;                  float* const g_h, u16* const g_hb, float* const g_out, const int final_out) {
;     ...
;       const float rs = c.use_rs ? rsqrtf(rss[r] * invK + 1e-6f) : 1.f;
;       if (c.epi == EPI_QKV) {
;         f32x4 x = v * rs;
;         float s = x[0] * x[0] + x[1] * x[1] + x[2] * x[2] + x[3] * x[3];
;         s += shx(s, 1, ln_); s += shx(s, 2, ln_); s += shx(s, 4, ln_); s += shx(s, 8, ln_);
;         if (g < c.nk_end) {
;           const float r2 = rsqrtf(s * (1.f / 64.f) + 1e-6f) * (g < 8 ? 0.125f * LOG2E : 1.f);
;           f32x4 gn = *(const f32x4*)(c.gain + (g < 8 ? 0 : 64) + (c4 & 63));
;           x = x * gn * r2;
;         }
.Lqkv2_pfd:
	s_nop 0
	v_writelane_b32 v255, s9, 51
	s_lshl_b32 s4, s92, 1
	s_mov_b64 s[8:9], 0
	s_waitcnt lgkmcnt(0)
	v_fmaak_f32 v226, v191, v226, 0x358637bd
	v_fmaak_f32 v227, v191, v227, 0x358637bd
	v_rsq_f32_e32 v226, v226
	v_rsq_f32_e32 v227, v227
	s_nop 0
	v_fmaak_f32 v228, v191, v228, 0x358637bd
	v_fmaak_f32 v229, v191, v229, 0x358637bd
	v_rsq_f32_e32 v228, v228
	v_rsq_f32_e32 v229, v229
	s_nop 0
	v_fmaak_f32 v230, v191, v230, 0x358637bd
	v_fmaak_f32 v231, v191, v231, 0x358637bd
	v_rsq_f32_e32 v230, v230
	v_rsq_f32_e32 v231, v231
	s_nop 0
	v_fmaak_f32 v232, v191, v232, 0x358637bd
	v_fmaak_f32 v233, v191, v233, 0x358637bd
	v_rsq_f32_e32 v232, v232
	v_rsq_f32_e32 v233, v233
	s_nop 0
	v_fmaak_f32 v234, v191, v234, 0x358637bd
	v_fmaak_f32 v235, v191, v235, 0x358637bd
	v_rsq_f32_e32 v234, v234
	v_rsq_f32_e32 v235, v235
	s_nop 0
	v_fmaak_f32 v236, v191, v236, 0x358637bd
	v_fmaak_f32 v237, v191, v237, 0x358637bd
	v_rsq_f32_e32 v236, v236
	v_rsq_f32_e32 v237, v237
	s_nop 0
	v_fmaak_f32 v238, v191, v238, 0x358637bd
	v_fmaak_f32 v239, v191, v239, 0x358637bd
	v_rsq_f32_e32 v238, v238
	v_rsq_f32_e32 v239, v239
	s_nop 0
	v_fmaak_f32 v240, v191, v240, 0x358637bd
	v_fmaak_f32 v241, v191, v241, 0x358637bd
	v_rsq_f32_e32 v240, v240
	v_rsq_f32_e32 v241, v241
	s_nop 0
	v_pk_mul_f32 v[64:65], v[64:65], v[226:227]
	v_pk_mul_f32 v[66:67], v[66:67], v[228:229]
	v_pk_mul_f32 v[68:69], v[68:69], v[226:227]
	v_pk_mul_f32 v[70:71], v[70:71], v[228:229]
	v_pk_mul_f32 v[72:73], v[72:73], v[226:227]
	v_pk_mul_f32 v[74:75], v[74:75], v[228:229]
	v_pk_mul_f32 v[76:77], v[76:77], v[226:227]
	v_pk_mul_f32 v[78:79], v[78:79], v[228:229]
	v_pk_mul_f32 v[80:81], v[80:81], v[226:227]
	v_pk_mul_f32 v[82:83], v[82:83], v[228:229]
	v_pk_mul_f32 v[84:85], v[84:85], v[226:227]
	v_pk_mul_f32 v[86:87], v[86:87], v[228:229]
	v_pk_mul_f32 v[88:89], v[88:89], v[226:227]
	v_pk_mul_f32 v[90:91], v[90:91], v[228:229]
	v_pk_mul_f32 v[92:93], v[92:93], v[226:227]
	v_pk_mul_f32 v[94:95], v[94:95], v[228:229]
	s_and_b64 vcc, exec, s[72:73]
	s_cbranch_vccz .Lqkv2_plain0
	v_mul_f32_e32 v246, v64, v64
	v_mul_f32_e32 v247, v65, v65
	v_mul_f32_e32 v248, v66, v66
	v_mul_f32_e32 v249, v67, v67
	v_fmac_f32_e32 v246, v68, v68
	v_fmac_f32_e32 v247, v69, v69
	v_fmac_f32_e32 v248, v70, v70
	v_fmac_f32_e32 v249, v71, v71
	v_fmac_f32_e32 v246, v72, v72
	v_fmac_f32_e32 v247, v73, v73
	v_fmac_f32_e32 v248, v74, v74
	v_fmac_f32_e32 v249, v75, v75
	v_fmac_f32_e32 v246, v76, v76
	v_fmac_f32_e32 v247, v77, v77
	v_fmac_f32_e32 v248, v78, v78
	v_fmac_f32_e32 v249, v79, v79
	v_add_f32_dpp v246, v246, v246 quad_perm:[1,0,3,2] row_mask:0xf bank_mask:0xf
	v_add_f32_dpp v247, v247, v247 quad_perm:[1,0,3,2] row_mask:0xf bank_mask:0xf
	v_add_f32_dpp v248, v248, v248 quad_perm:[1,0,3,2] row_mask:0xf bank_mask:0xf
	v_add_f32_dpp v249, v249, v249 quad_perm:[1,0,3,2] row_mask:0xf bank_mask:0xf
	v_add_f32_dpp v246, v246, v246 quad_perm:[2,3,0,1] row_mask:0xf bank_mask:0xf
	v_add_f32_dpp v247, v247, v247 quad_perm:[2,3,0,1] row_mask:0xf bank_mask:0xf
	v_add_f32_dpp v248, v248, v248 quad_perm:[2,3,0,1] row_mask:0xf bank_mask:0xf
	v_add_f32_dpp v249, v249, v249 quad_perm:[2,3,0,1] row_mask:0xf bank_mask:0xf
	v_add_f32_dpp v246, v246, v246 row_half_mirror row_mask:0xf bank_mask:0xf
	v_add_f32_dpp v247, v247, v247 row_half_mirror row_mask:0xf bank_mask:0xf
	v_add_f32_dpp v248, v248, v248 row_half_mirror row_mask:0xf bank_mask:0xf
	v_add_f32_dpp v249, v249, v249 row_half_mirror row_mask:0xf bank_mask:0xf
	v_add_f32_dpp v246, v246, v246 row_mirror row_mask:0xf bank_mask:0xf
	v_add_f32_dpp v247, v247, v247 row_mirror row_mask:0xf bank_mask:0xf
	v_add_f32_dpp v248, v248, v248 row_mirror row_mask:0xf bank_mask:0xf
	v_add_f32_dpp v249, v249, v249 row_mirror row_mask:0xf bank_mask:0xf
	v_fmaak_f32 v246, v250, v246, 0x358637bd
	v_fmaak_f32 v247, v250, v247, 0x358637bd
	v_rsq_f32_e32 v246, v246
	v_rsq_f32_e32 v247, v247
	s_nop 0
	v_mul_f32_e32 v246, v148, v246
	v_mul_f32_e32 v247, v148, v247
	v_fmaak_f32 v248, v250, v248, 0x358637bd
	v_fmaak_f32 v249, v250, v249, 0x358637bd
	v_rsq_f32_e32 v248, v248
	v_rsq_f32_e32 v249, v249
	s_nop 0
	v_mul_f32_e32 v248, v148, v248
	v_mul_f32_e32 v249, v148, v249
	v_pk_mul_f32 v[64:65], v[64:65], v[246:247]
	v_pk_mul_f32 v[66:67], v[66:67], v[248:249]
	v_pk_mul_f32 v[64:65], v[64:65], v[140:141] op_sel_hi:[1,0]
	v_pk_mul_f32 v[66:67], v[66:67], v[140:141] op_sel_hi:[1,0]
	v_pk_mul_f32 v[68:69], v[68:69], v[246:247]
	v_pk_mul_f32 v[70:71], v[70:71], v[248:249]
	v_pk_mul_f32 v[68:69], v[68:69], v[142:143] op_sel_hi:[1,0]
	v_pk_mul_f32 v[70:71], v[70:71], v[142:143] op_sel_hi:[1,0]
	v_pk_mul_f32 v[72:73], v[72:73], v[246:247]
	v_pk_mul_f32 v[74:75], v[74:75], v[248:249]
	v_pk_mul_f32 v[72:73], v[72:73], v[144:145] op_sel_hi:[1,0]
	v_pk_mul_f32 v[74:75], v[74:75], v[144:145] op_sel_hi:[1,0]
	v_pk_mul_f32 v[76:77], v[76:77], v[246:247]
	v_pk_mul_f32 v[78:79], v[78:79], v[248:249]
	v_pk_mul_f32 v[76:77], v[76:77], v[146:147] op_sel_hi:[1,0]
	v_pk_mul_f32 v[78:79], v[78:79], v[146:147] op_sel_hi:[1,0]
	v_mul_f32_e32 v246, v80, v80
	v_mul_f32_e32 v247, v81, v81
	v_mul_f32_e32 v248, v82, v82
	v_mul_f32_e32 v249, v83, v83
	v_fmac_f32_e32 v246, v84, v84
	v_fmac_f32_e32 v247, v85, v85
	v_fmac_f32_e32 v248, v86, v86
	v_fmac_f32_e32 v249, v87, v87
	v_fmac_f32_e32 v246, v88, v88
	v_fmac_f32_e32 v247, v89, v89
	v_fmac_f32_e32 v248, v90, v90
	v_fmac_f32_e32 v249, v91, v91
	v_fmac_f32_e32 v246, v92, v92
	v_fmac_f32_e32 v247, v93, v93
	v_fmac_f32_e32 v248, v94, v94
	v_fmac_f32_e32 v249, v95, v95
	v_add_f32_dpp v246, v246, v246 quad_perm:[1,0,3,2] row_mask:0xf bank_mask:0xf
	v_add_f32_dpp v247, v247, v247 quad_perm:[1,0,3,2] row_mask:0xf bank_mask:0xf
; DI float shx(float v, int mask, int lane) { return __int_as_float(__builtin_amdgcn_ds_bpermute((lane ^ mask) << 2, __float_as_int(v))); }
; DI void epi_slab(const GemmCfg c, const f32x16 (&acc)[4], float* sW, const float* rss, const size_t row0, const int g, const int lane,
;                  float* const g_h, u16* const g_hb, float* const g_out, const int final_out) {
;     ...
;       const float rs = c.use_rs ? rsqrtf(rss[r] * invK + 1e-6f) : 1.f;
;       if (c.epi == EPI_QKV) {
;         f32x4 x = v * rs;
;         float s = x[0] * x[0] + x[1] * x[1] + x[2] * x[2] + x[3] * x[3];
;         s += shx(s, 1, ln_); s += shx(s, 2, ln_); s += shx(s, 4, ln_); s += shx(s, 8, ln_);
;         if (g < c.nk_end) {
;           const float r2 = rsqrtf(s * (1.f / 64.f) + 1e-6f) * (g < 8 ? 0.125f * LOG2E : 1.f);
;           f32x4 gn = *(const f32x4*)(c.gain + (g < 8 ? 0 : 64) + (c4 & 63));
;           x = x * gn * r2;
;         }
;         *(u32x2*)(c.o16 + row * c.ldo + col) = MK2(pack2(x[0], x[1]), pack2(x[2], x[3]));
	v_add_f32_dpp v248, v248, v248 quad_perm:[1,0,3,2] row_mask:0xf bank_mask:0xf
	v_add_f32_dpp v249, v249, v249 quad_perm:[1,0,3,2] row_mask:0xf bank_mask:0xf
	v_add_f32_dpp v246, v246, v246 quad_perm:[2,3,0,1] row_mask:0xf bank_mask:0xf
	v_add_f32_dpp v247, v247, v247 quad_perm:[2,3,0,1] row_mask:0xf bank_mask:0xf
	v_add_f32_dpp v248, v248, v248 quad_perm:[2,3,0,1] row_mask:0xf bank_mask:0xf
	v_add_f32_dpp v249, v249, v249 quad_perm:[2,3,0,1] row_mask:0xf bank_mask:0xf
	v_add_f32_dpp v246, v246, v246 row_half_mirror row_mask:0xf bank_mask:0xf
	v_add_f32_dpp v247, v247, v247 row_half_mirror row_mask:0xf bank_mask:0xf
	v_add_f32_dpp v248, v248, v248 row_half_mirror row_mask:0xf bank_mask:0xf
	v_add_f32_dpp v249, v249, v249 row_half_mirror row_mask:0xf bank_mask:0xf
	v_add_f32_dpp v246, v246, v246 row_mirror row_mask:0xf bank_mask:0xf
	v_add_f32_dpp v247, v247, v247 row_mirror row_mask:0xf bank_mask:0xf
	v_add_f32_dpp v248, v248, v248 row_mirror row_mask:0xf bank_mask:0xf
	v_add_f32_dpp v249, v249, v249 row_mirror row_mask:0xf bank_mask:0xf
	v_fmaak_f32 v246, v250, v246, 0x358637bd
	v_fmaak_f32 v247, v250, v247, 0x358637bd
	v_rsq_f32_e32 v246, v246
	v_rsq_f32_e32 v247, v247
	s_nop 0
	v_mul_f32_e32 v246, v148, v246
	v_mul_f32_e32 v247, v148, v247
	v_fmaak_f32 v248, v250, v248, 0x358637bd
	v_fmaak_f32 v249, v250, v249, 0x358637bd
	v_rsq_f32_e32 v248, v248
	v_rsq_f32_e32 v249, v249
	s_nop 0
	v_mul_f32_e32 v248, v148, v248
	v_mul_f32_e32 v249, v148, v249
	v_pk_mul_f32 v[80:81], v[80:81], v[246:247]
	v_pk_mul_f32 v[82:83], v[82:83], v[248:249]
	v_pk_mul_f32 v[80:81], v[80:81], v[140:141] op_sel_hi:[1,0]
	v_pk_mul_f32 v[82:83], v[82:83], v[140:141] op_sel_hi:[1,0]
	v_pk_mul_f32 v[84:85], v[84:85], v[246:247]
	v_pk_mul_f32 v[86:87], v[86:87], v[248:249]
	v_pk_mul_f32 v[84:85], v[84:85], v[142:143] op_sel_hi:[1,0]
	v_pk_mul_f32 v[86:87], v[86:87], v[142:143] op_sel_hi:[1,0]
	v_pk_mul_f32 v[88:89], v[88:89], v[246:247]
	v_pk_mul_f32 v[90:91], v[90:91], v[248:249]
	v_pk_mul_f32 v[88:89], v[88:89], v[144:145] op_sel_hi:[1,0]
	v_pk_mul_f32 v[90:91], v[90:91], v[144:145] op_sel_hi:[1,0]
	v_pk_mul_f32 v[92:93], v[92:93], v[246:247]
	v_pk_mul_f32 v[94:95], v[94:95], v[248:249]
	v_pk_mul_f32 v[92:93], v[92:93], v[146:147] op_sel_hi:[1,0]
	v_pk_mul_f32 v[94:95], v[94:95], v[146:147] op_sel_hi:[1,0]
.Lqkv2_plain0:
	ds_write2_b32 v198, v64, v65 offset0:0 offset1:132
	ds_write2_b32 v199, v66, v67 offset0:0 offset1:132
	ds_write2_b32 v198, v68, v69 offset0:16 offset1:148
	ds_write2_b32 v199, v70, v71 offset0:16 offset1:148
	ds_write2_b32 v198, v72, v73 offset0:32 offset1:164
	ds_write2_b32 v199, v74, v75 offset0:32 offset1:164
	ds_write2_b32 v198, v76, v77 offset0:48 offset1:180
	ds_write2_b32 v199, v78, v79 offset0:48 offset1:180
	ds_write2_b32 v198, v80, v81 offset0:64 offset1:196
	ds_write2_b32 v199, v82, v83 offset0:64 offset1:196
	ds_write2_b32 v198, v84, v85 offset0:80 offset1:212
	ds_write2_b32 v199, v86, v87 offset0:80 offset1:212
	ds_write2_b32 v198, v88, v89 offset0:96 offset1:228
	ds_write2_b32 v199, v90, v91 offset0:96 offset1:228
	ds_write2_b32 v198, v92, v93 offset0:112 offset1:244
	ds_write2_b32 v199, v94, v95 offset0:112 offset1:244
	s_waitcnt lgkmcnt(0)
	ds_read_b128 v[64:67], v202
	ds_read_b128 v[68:71], v202 offset:1056
	ds_read_b128 v[72:75], v202 offset:2112
	ds_read_b128 v[76:79], v202 offset:3168
	ds_read_b128 v[80:83], v202 offset:4224
	ds_read_b128 v[84:87], v202 offset:5280
	ds_read_b128 v[88:91], v202 offset:6336
	ds_read_b128 v[92:95], v202 offset:7392
	s_waitcnt lgkmcnt(7)
	v_lshl_add_u64 v[206:207], v[204:205], 0, s[8:9]
	v_cvt_pk_bf16_f32 v64, v64, v65
	v_cvt_pk_bf16_f32 v65, v66, v67
	s_add_u32 s8, s8, s4
	s_addc_u32 s9, s9, 0
	global_store_dwordx2 v[206:207], v[64:65], off
	s_waitcnt lgkmcnt(6)
	v_lshl_add_u64 v[206:207], v[204:205], 0, s[8:9]
	v_cvt_pk_bf16_f32 v68, v68, v69
	v_cvt_pk_bf16_f32 v69, v70, v71
	s_add_u32 s8, s8, s4
	s_addc_u32 s9, s9, 0
	global_store_dwordx2 v[206:207], v[68:69], off
	s_waitcnt lgkmcnt(5)
	v_lshl_add_u64 v[206:207], v[204:205], 0, s[8:9]
	v_cvt_pk_bf16_f32 v72, v72, v73
	v_cvt_pk_bf16_f32 v73, v74, v75
	s_add_u32 s8, s8, s4
	s_addc_u32 s9, s9, 0
	global_store_dwordx2 v[206:207], v[72:73], off
	s_waitcnt lgkmcnt(4)
	v_lshl_add_u64 v[206:207], v[204:205], 0, s[8:9]
	v_cvt_pk_bf16_f32 v76, v76, v77
	v_cvt_pk_bf16_f32 v77, v78, v79
	s_add_u32 s8, s8, s4
	s_addc_u32 s9, s9, 0
	global_store_dwordx2 v[206:207], v[76:77], off
	s_waitcnt lgkmcnt(3)
	v_lshl_add_u64 v[206:207], v[204:205], 0, s[8:9]
	v_cvt_pk_bf16_f32 v80, v80, v81
	v_cvt_pk_bf16_f32 v81, v82, v83
	s_add_u32 s8, s8, s4
	s_addc_u32 s9, s9, 0
	global_store_dwordx2 v[206:207], v[80:81], off
	s_waitcnt lgkmcnt(2)
	v_lshl_add_u64 v[206:207], v[204:205], 0, s[8:9]
	v_cvt_pk_bf16_f32 v84, v84, v85
	v_cvt_pk_bf16_f32 v85, v86, v87
	s_add_u32 s8, s8, s4
	s_addc_u32 s9, s9, 0
	global_store_dwordx2 v[206:207], v[84:85], off
	s_waitcnt lgkmcnt(1)
	v_lshl_add_u64 v[206:207], v[204:205], 0, s[8:9]
	v_cvt_pk_bf16_f32 v88, v88, v89
	v_cvt_pk_bf16_f32 v89, v90, v91
	s_add_u32 s8, s8, s4
	s_addc_u32 s9, s9, 0
	global_store_dwordx2 v[206:207], v[88:89], off
	s_waitcnt lgkmcnt(0)
	v_lshl_add_u64 v[206:207], v[204:205], 0, s[8:9]
	v_cvt_pk_bf16_f32 v92, v92, v93
	v_cvt_pk_bf16_f32 v93, v94, v95
	s_add_u32 s8, s8, s4
	s_addc_u32 s9, s9, 0
	global_store_dwordx2 v[206:207], v[92:93], off
	v_pk_mul_f32 v[96:97], v[96:97], v[230:231]
	v_pk_mul_f32 v[98:99], v[98:99], v[232:233]
	v_pk_mul_f32 v[100:101], v[100:101], v[230:231]
	v_pk_mul_f32 v[102:103], v[102:103], v[232:233]
	v_pk_mul_f32 v[104:105], v[104:105], v[230:231]
	v_pk_mul_f32 v[106:107], v[106:107], v[232:233]
	v_pk_mul_f32 v[108:109], v[108:109], v[230:231]
	v_pk_mul_f32 v[110:111], v[110:111], v[232:233]
	v_pk_mul_f32 v[112:113], v[112:113], v[230:231]
	v_pk_mul_f32 v[114:115], v[114:115], v[232:233]
	v_pk_mul_f32 v[116:117], v[116:117], v[230:231]
	v_pk_mul_f32 v[118:119], v[118:119], v[232:233]
	v_pk_mul_f32 v[120:121], v[120:121], v[230:231]
	v_pk_mul_f32 v[122:123], v[122:123], v[232:233]
	v_pk_mul_f32 v[124:125], v[124:125], v[230:231]
	v_pk_mul_f32 v[126:127], v[126:127], v[232:233]
	s_and_b64 vcc, exec, s[72:73]
	s_cbranch_vccz .Lqkv2_plain1
; DI float shx(float v, int mask, int lane) { return __int_as_float(__builtin_amdgcn_ds_bpermute((lane ^ mask) << 2, __float_as_int(v))); }
; DI void epi_slab(const GemmCfg c, const f32x16 (&acc)[4], float* sW, const float* rss, const size_t row0, const int g, const int lane,
;                  float* const g_h, u16* const g_hb, float* const g_out, const int final_out) {
;     ...
;       const float rs = c.use_rs ? rsqrtf(rss[r] * invK + 1e-6f) : 1.f;
;       if (c.epi == EPI_QKV) {
;         f32x4 x = v * rs;
;         float s = x[0] * x[0] + x[1] * x[1] + x[2] * x[2] + x[3] * x[3];
;         s += shx(s, 1, ln_); s += shx(s, 2, ln_); s += shx(s, 4, ln_); s += shx(s, 8, ln_);
;         if (g < c.nk_end) {
;           const float r2 = rsqrtf(s * (1.f / 64.f) + 1e-6f) * (g < 8 ? 0.125f * LOG2E : 1.f);
;           f32x4 gn = *(const f32x4*)(c.gain + (g < 8 ? 0 : 64) + (c4 & 63));
;           x = x * gn * r2;
;         }
	v_mul_f32_e32 v246, v96, v96
	v_mul_f32_e32 v247, v97, v97
	v_mul_f32_e32 v248, v98, v98
	v_mul_f32_e32 v249, v99, v99
	v_fmac_f32_e32 v246, v100, v100
	v_fmac_f32_e32 v247, v101, v101
	v_fmac_f32_e32 v248, v102, v102
	v_fmac_f32_e32 v249, v103, v103
	v_fmac_f32_e32 v246, v104, v104
	v_fmac_f32_e32 v247, v105, v105
	v_fmac_f32_e32 v248, v106, v106
	v_fmac_f32_e32 v249, v107, v107
	v_fmac_f32_e32 v246, v108, v108
	v_fmac_f32_e32 v247, v109, v109
	v_fmac_f32_e32 v248, v110, v110
	v_fmac_f32_e32 v249, v111, v111
	v_add_f32_dpp v246, v246, v246 quad_perm:[1,0,3,2] row_mask:0xf bank_mask:0xf
	v_add_f32_dpp v247, v247, v247 quad_perm:[1,0,3,2] row_mask:0xf bank_mask:0xf
	v_add_f32_dpp v248, v248, v248 quad_perm:[1,0,3,2] row_mask:0xf bank_mask:0xf
	v_add_f32_dpp v249, v249, v249 quad_perm:[1,0,3,2] row_mask:0xf bank_mask:0xf
	v_add_f32_dpp v246, v246, v246 quad_perm:[2,3,0,1] row_mask:0xf bank_mask:0xf
	v_add_f32_dpp v247, v247, v247 quad_perm:[2,3,0,1] row_mask:0xf bank_mask:0xf
	v_add_f32_dpp v248, v248, v248 quad_perm:[2,3,0,1] row_mask:0xf bank_mask:0xf
	v_add_f32_dpp v249, v249, v249 quad_perm:[2,3,0,1] row_mask:0xf bank_mask:0xf
	v_add_f32_dpp v246, v246, v246 row_half_mirror row_mask:0xf bank_mask:0xf
	v_add_f32_dpp v247, v247, v247 row_half_mirror row_mask:0xf bank_mask:0xf
	v_add_f32_dpp v248, v248, v248 row_half_mirror row_mask:0xf bank_mask:0xf
	v_add_f32_dpp v249, v249, v249 row_half_mirror row_mask:0xf bank_mask:0xf
	v_add_f32_dpp v246, v246, v246 row_mirror row_mask:0xf bank_mask:0xf
	v_add_f32_dpp v247, v247, v247 row_mirror row_mask:0xf bank_mask:0xf
	v_add_f32_dpp v248, v248, v248 row_mirror row_mask:0xf bank_mask:0xf
	v_add_f32_dpp v249, v249, v249 row_mirror row_mask:0xf bank_mask:0xf
	v_fmaak_f32 v246, v250, v246, 0x358637bd
	v_fmaak_f32 v247, v250, v247, 0x358637bd
	v_rsq_f32_e32 v246, v246
	v_rsq_f32_e32 v247, v247
	s_nop 0
	v_mul_f32_e32 v246, v148, v246
	v_mul_f32_e32 v247, v148, v247
	v_fmaak_f32 v248, v250, v248, 0x358637bd
	v_fmaak_f32 v249, v250, v249, 0x358637bd
	v_rsq_f32_e32 v248, v248
	v_rsq_f32_e32 v249, v249
	s_nop 0
	v_mul_f32_e32 v248, v148, v248
	v_mul_f32_e32 v249, v148, v249
	v_pk_mul_f32 v[96:97], v[96:97], v[246:247]
	v_pk_mul_f32 v[98:99], v[98:99], v[248:249]
	v_pk_mul_f32 v[96:97], v[96:97], v[140:141] op_sel_hi:[1,0]
	v_pk_mul_f32 v[98:99], v[98:99], v[140:141] op_sel_hi:[1,0]
	v_pk_mul_f32 v[100:101], v[100:101], v[246:247]
	v_pk_mul_f32 v[102:103], v[102:103], v[248:249]
	v_pk_mul_f32 v[100:101], v[100:101], v[142:143] op_sel_hi:[1,0]
	v_pk_mul_f32 v[102:103], v[102:103], v[142:143] op_sel_hi:[1,0]
	v_pk_mul_f32 v[104:105], v[104:105], v[246:247]
	v_pk_mul_f32 v[106:107], v[106:107], v[248:249]
	v_pk_mul_f32 v[104:105], v[104:105], v[144:145] op_sel_hi:[1,0]
	v_pk_mul_f32 v[106:107], v[106:107], v[144:145] op_sel_hi:[1,0]
	v_pk_mul_f32 v[108:109], v[108:109], v[246:247]
	v_pk_mul_f32 v[110:111], v[110:111], v[248:249]
	v_pk_mul_f32 v[108:109], v[108:109], v[146:147] op_sel_hi:[1,0]
	v_pk_mul_f32 v[110:111], v[110:111], v[146:147] op_sel_hi:[1,0]
	v_mul_f32_e32 v246, v112, v112
	v_mul_f32_e32 v247, v113, v113
	v_mul_f32_e32 v248, v114, v114
	v_mul_f32_e32 v249, v115, v115
	v_fmac_f32_e32 v246, v116, v116
	v_fmac_f32_e32 v247, v117, v117
	v_fmac_f32_e32 v248, v118, v118
	v_fmac_f32_e32 v249, v119, v119
	v_fmac_f32_e32 v246, v120, v120
	v_fmac_f32_e32 v247, v121, v121
	v_fmac_f32_e32 v248, v122, v122
	v_fmac_f32_e32 v249, v123, v123
	v_fmac_f32_e32 v246, v124, v124
	v_fmac_f32_e32 v247, v125, v125
	v_fmac_f32_e32 v248, v126, v126
	v_fmac_f32_e32 v249, v127, v127
	v_add_f32_dpp v246, v246, v246 quad_perm:[1,0,3,2] row_mask:0xf bank_mask:0xf
	v_add_f32_dpp v247, v247, v247 quad_perm:[1,0,3,2] row_mask:0xf bank_mask:0xf
	v_add_f32_dpp v248, v248, v248 quad_perm:[1,0,3,2] row_mask:0xf bank_mask:0xf
	v_add_f32_dpp v249, v249, v249 quad_perm:[1,0,3,2] row_mask:0xf bank_mask:0xf
	v_add_f32_dpp v246, v246, v246 quad_perm:[2,3,0,1] row_mask:0xf bank_mask:0xf
	v_add_f32_dpp v247, v247, v247 quad_perm:[2,3,0,1] row_mask:0xf bank_mask:0xf
	v_add_f32_dpp v248, v248, v248 quad_perm:[2,3,0,1] row_mask:0xf bank_mask:0xf
	v_add_f32_dpp v249, v249, v249 quad_perm:[2,3,0,1] row_mask:0xf bank_mask:0xf
	v_add_f32_dpp v246, v246, v246 row_half_mirror row_mask:0xf bank_mask:0xf
	v_add_f32_dpp v247, v247, v247 row_half_mirror row_mask:0xf bank_mask:0xf
	v_add_f32_dpp v248, v248, v248 row_half_mirror row_mask:0xf bank_mask:0xf
	v_add_f32_dpp v249, v249, v249 row_half_mirror row_mask:0xf bank_mask:0xf
	v_add_f32_dpp v246, v246, v246 row_mirror row_mask:0xf bank_mask:0xf
	v_add_f32_dpp v247, v247, v247 row_mirror row_mask:0xf bank_mask:0xf
	v_add_f32_dpp v248, v248, v248 row_mirror row_mask:0xf bank_mask:0xf
	v_add_f32_dpp v249, v249, v249 row_mirror row_mask:0xf bank_mask:0xf
	v_fmaak_f32 v246, v250, v246, 0x358637bd
	v_fmaak_f32 v247, v250, v247, 0x358637bd
	v_rsq_f32_e32 v246, v246
	v_rsq_f32_e32 v247, v247
	s_nop 0
	v_mul_f32_e32 v246, v148, v246
	v_mul_f32_e32 v247, v148, v247
	v_fmaak_f32 v248, v250, v248, 0x358637bd
	v_fmaak_f32 v249, v250, v249, 0x358637bd
	v_rsq_f32_e32 v248, v248
	v_rsq_f32_e32 v249, v249
	s_nop 0
	v_mul_f32_e32 v248, v148, v248
	v_mul_f32_e32 v249, v148, v249
	v_pk_mul_f32 v[112:113], v[112:113], v[246:247]
	v_pk_mul_f32 v[114:115], v[114:115], v[248:249]
	v_pk_mul_f32 v[112:113], v[112:113], v[140:141] op_sel_hi:[1,0]
	v_pk_mul_f32 v[114:115], v[114:115], v[140:141] op_sel_hi:[1,0]
	v_pk_mul_f32 v[116:117], v[116:117], v[246:247]
	v_pk_mul_f32 v[118:119], v[118:119], v[248:249]
	v_pk_mul_f32 v[116:117], v[116:117], v[142:143] op_sel_hi:[1,0]
	v_pk_mul_f32 v[118:119], v[118:119], v[142:143] op_sel_hi:[1,0]
	v_pk_mul_f32 v[120:121], v[120:121], v[246:247]
	v_pk_mul_f32 v[122:123], v[122:123], v[248:249]
	v_pk_mul_f32 v[120:121], v[120:121], v[144:145] op_sel_hi:[1,0]
	v_pk_mul_f32 v[122:123], v[122:123], v[144:145] op_sel_hi:[1,0]
	v_pk_mul_f32 v[124:125], v[124:125], v[246:247]
	v_pk_mul_f32 v[126:127], v[126:127], v[248:249]
	v_pk_mul_f32 v[124:125], v[124:125], v[146:147] op_sel_hi:[1,0]
	v_pk_mul_f32 v[126:127], v[126:127], v[146:147] op_sel_hi:[1,0]
; DI float shx(float v, int mask, int lane) { return __int_as_float(__builtin_amdgcn_ds_bpermute((lane ^ mask) << 2, __float_as_int(v))); }
; DI int crow(int i, int hh) { return (i & 3) + 8 * (i >> 2) + 4 * hh; }
; DI void epi_slab(const GemmCfg c, const f32x16 (&acc)[4], float* sW, const float* rss, const size_t row0, const int g, const int lane,
;                  float* const g_h, u16* const g_hb, float* const g_out, const int final_out) {
;     ...
;   for (int nb = 0; nb < 4; ++nb)
; #pragma unroll
;     for (int i = 0; i < 16; ++i) sW[crow(i, hh) * 132 + nb * 32 + l31] = acc[nb][i];
;     ...
;       if (c.epi == EPI_QKV) {
;         f32x4 x = v * rs;
;         float s = x[0] * x[0] + x[1] * x[1] + x[2] * x[2] + x[3] * x[3];
;         s += shx(s, 1, ln_); s += shx(s, 2, ln_); s += shx(s, 4, ln_); s += shx(s, 8, ln_);
;         if (g < c.nk_end) {
;           const float r2 = rsqrtf(s * (1.f / 64.f) + 1e-6f) * (g < 8 ? 0.125f * LOG2E : 1.f);
;           f32x4 gn = *(const f32x4*)(c.gain + (g < 8 ? 0 : 64) + (c4 & 63));
;           x = x * gn * r2;
;         }
;         *(u32x2*)(c.o16 + row * c.ldo + col) = MK2(pack2(x[0], x[1]), pack2(x[2], x[3]));
.Lqkv2_plain1:
	ds_write2_b32 v198, v96, v97 offset0:0 offset1:132
	ds_write2_b32 v199, v98, v99 offset0:0 offset1:132
	ds_write2_b32 v198, v100, v101 offset0:16 offset1:148
	ds_write2_b32 v199, v102, v103 offset0:16 offset1:148
	ds_write2_b32 v198, v104, v105 offset0:32 offset1:164
	ds_write2_b32 v199, v106, v107 offset0:32 offset1:164
	ds_write2_b32 v198, v108, v109 offset0:48 offset1:180
	ds_write2_b32 v199, v110, v111 offset0:48 offset1:180
	ds_write2_b32 v198, v112, v113 offset0:64 offset1:196
	ds_write2_b32 v199, v114, v115 offset0:64 offset1:196
	ds_write2_b32 v198, v116, v117 offset0:80 offset1:212
	ds_write2_b32 v199, v118, v119 offset0:80 offset1:212
	ds_write2_b32 v198, v120, v121 offset0:96 offset1:228
	ds_write2_b32 v199, v122, v123 offset0:96 offset1:228
	ds_write2_b32 v198, v124, v125 offset0:112 offset1:244
	ds_write2_b32 v199, v126, v127 offset0:112 offset1:244
	s_waitcnt lgkmcnt(0)
	ds_read_b128 v[96:99], v202
	ds_read_b128 v[100:103], v202 offset:1056
	ds_read_b128 v[104:107], v202 offset:2112
	ds_read_b128 v[108:111], v202 offset:3168
	ds_read_b128 v[112:115], v202 offset:4224
	ds_read_b128 v[116:119], v202 offset:5280
	ds_read_b128 v[120:123], v202 offset:6336
	ds_read_b128 v[124:127], v202 offset:7392
	s_waitcnt lgkmcnt(7)
	v_lshl_add_u64 v[206:207], v[204:205], 0, s[8:9]
	v_cvt_pk_bf16_f32 v96, v96, v97
	v_cvt_pk_bf16_f32 v97, v98, v99
	s_add_u32 s8, s8, s4
	s_addc_u32 s9, s9, 0
	global_store_dwordx2 v[206:207], v[96:97], off
	s_waitcnt lgkmcnt(6)
	v_lshl_add_u64 v[206:207], v[204:205], 0, s[8:9]
	v_cvt_pk_bf16_f32 v100, v100, v101
	v_cvt_pk_bf16_f32 v101, v102, v103
	s_add_u32 s8, s8, s4
	s_addc_u32 s9, s9, 0
	global_store_dwordx2 v[206:207], v[100:101], off
	s_waitcnt lgkmcnt(5)
	v_lshl_add_u64 v[206:207], v[204:205], 0, s[8:9]
	v_cvt_pk_bf16_f32 v104, v104, v105
	v_cvt_pk_bf16_f32 v105, v106, v107
	s_add_u32 s8, s8, s4
	s_addc_u32 s9, s9, 0
	global_store_dwordx2 v[206:207], v[104:105], off
	s_waitcnt lgkmcnt(4)
	v_lshl_add_u64 v[206:207], v[204:205], 0, s[8:9]
	v_cvt_pk_bf16_f32 v108, v108, v109
	v_cvt_pk_bf16_f32 v109, v110, v111
	s_add_u32 s8, s8, s4
	s_addc_u32 s9, s9, 0
	global_store_dwordx2 v[206:207], v[108:109], off
	s_waitcnt lgkmcnt(3)
	v_lshl_add_u64 v[206:207], v[204:205], 0, s[8:9]
	v_cvt_pk_bf16_f32 v112, v112, v113
	v_cvt_pk_bf16_f32 v113, v114, v115
	s_add_u32 s8, s8, s4
	s_addc_u32 s9, s9, 0
	global_store_dwordx2 v[206:207], v[112:113], off
	s_waitcnt lgkmcnt(2)
	v_lshl_add_u64 v[206:207], v[204:205], 0, s[8:9]
	v_cvt_pk_bf16_f32 v116, v116, v117
	v_cvt_pk_bf16_f32 v117, v118, v119
	s_add_u32 s8, s8, s4
	s_addc_u32 s9, s9, 0
	global_store_dwordx2 v[206:207], v[116:117], off
	s_waitcnt lgkmcnt(1)
	v_lshl_add_u64 v[206:207], v[204:205], 0, s[8:9]
	v_cvt_pk_bf16_f32 v120, v120, v121
	v_cvt_pk_bf16_f32 v121, v122, v123
	s_add_u32 s8, s8, s4
	s_addc_u32 s9, s9, 0
	global_store_dwordx2 v[206:207], v[120:121], off
	s_waitcnt lgkmcnt(0)
	v_lshl_add_u64 v[206:207], v[204:205], 0, s[8:9]
	v_cvt_pk_bf16_f32 v124, v124, v125
	v_cvt_pk_bf16_f32 v125, v126, v127
	s_add_u32 s8, s8, s4
	s_addc_u32 s9, s9, 0
	global_store_dwordx2 v[206:207], v[124:125], off
	v_pk_mul_f32 v[0:1], v[0:1], v[234:235]
	v_pk_mul_f32 v[2:3], v[2:3], v[236:237]
	v_pk_mul_f32 v[4:5], v[4:5], v[234:235]
	v_pk_mul_f32 v[6:7], v[6:7], v[236:237]
	v_pk_mul_f32 v[8:9], v[8:9], v[234:235]
	v_pk_mul_f32 v[10:11], v[10:11], v[236:237]
	v_pk_mul_f32 v[12:13], v[12:13], v[234:235]
	v_pk_mul_f32 v[14:15], v[14:15], v[236:237]
	v_pk_mul_f32 v[16:17], v[16:17], v[234:235]
	v_pk_mul_f32 v[18:19], v[18:19], v[236:237]
	v_pk_mul_f32 v[20:21], v[20:21], v[234:235]
	v_pk_mul_f32 v[22:23], v[22:23], v[236:237]
	v_pk_mul_f32 v[24:25], v[24:25], v[234:235]
	v_pk_mul_f32 v[26:27], v[26:27], v[236:237]
	v_pk_mul_f32 v[28:29], v[28:29], v[234:235]
	v_pk_mul_f32 v[30:31], v[30:31], v[236:237]
	s_and_b64 vcc, exec, s[72:73]
	s_cbranch_vccz .Lqkv2_plain2
	v_mul_f32_e32 v246, v0, v0
	v_mul_f32_e32 v247, v1, v1
	v_mul_f32_e32 v248, v2, v2
	v_mul_f32_e32 v249, v3, v3
	v_fmac_f32_e32 v246, v4, v4
	v_fmac_f32_e32 v247, v5, v5
	v_fmac_f32_e32 v248, v6, v6
	v_fmac_f32_e32 v249, v7, v7
	v_fmac_f32_e32 v246, v8, v8
	v_fmac_f32_e32 v247, v9, v9
	v_fmac_f32_e32 v248, v10, v10
	v_fmac_f32_e32 v249, v11, v11
	v_fmac_f32_e32 v246, v12, v12
	v_fmac_f32_e32 v247, v13, v13
	v_fmac_f32_e32 v248, v14, v14
	v_fmac_f32_e32 v249, v15, v15
	v_add_f32_dpp v246, v246, v246 quad_perm:[1,0,3,2] row_mask:0xf bank_mask:0xf
	v_add_f32_dpp v247, v247, v247 quad_perm:[1,0,3,2] row_mask:0xf bank_mask:0xf
	v_add_f32_dpp v248, v248, v248 quad_perm:[1,0,3,2] row_mask:0xf bank_mask:0xf
	v_add_f32_dpp v249, v249, v249 quad_perm:[1,0,3,2] row_mask:0xf bank_mask:0xf
	v_add_f32_dpp v246, v246, v246 quad_perm:[2,3,0,1] row_mask:0xf bank_mask:0xf
	v_add_f32_dpp v247, v247, v247 quad_perm:[2,3,0,1] row_mask:0xf bank_mask:0xf
	v_add_f32_dpp v248, v248, v248 quad_perm:[2,3,0,1] row_mask:0xf bank_mask:0xf
	v_add_f32_dpp v249, v249, v249 quad_perm:[2,3,0,1] row_mask:0xf bank_mask:0xf
	v_add_f32_dpp v246, v246, v246 row_half_mirror row_mask:0xf bank_mask:0xf
	v_add_f32_dpp v247, v247, v247 row_half_mirror row_mask:0xf bank_mask:0xf
	v_add_f32_dpp v248, v248, v248 row_half_mirror row_mask:0xf bank_mask:0xf
	v_add_f32_dpp v249, v249, v249 row_half_mirror row_mask:0xf bank_mask:0xf
	v_add_f32_dpp v246, v246, v246 row_mirror row_mask:0xf bank_mask:0xf
	v_add_f32_dpp v247, v247, v247 row_mirror row_mask:0xf bank_mask:0xf
	v_add_f32_dpp v248, v248, v248 row_mirror row_mask:0xf bank_mask:0xf
	v_add_f32_dpp v249, v249, v249 row_mirror row_mask:0xf bank_mask:0xf
	v_fmaak_f32 v246, v250, v246, 0x358637bd
; DI float shx(float v, int mask, int lane) { return __int_as_float(__builtin_amdgcn_ds_bpermute((lane ^ mask) << 2, __float_as_int(v))); }
; DI void epi_slab(const GemmCfg c, const f32x16 (&acc)[4], float* sW, const float* rss, const size_t row0, const int g, const int lane,
;                  float* const g_h, u16* const g_hb, float* const g_out, const int final_out) {
;     ...
;       if (c.epi == EPI_QKV) {
;         f32x4 x = v * rs;
;         float s = x[0] * x[0] + x[1] * x[1] + x[2] * x[2] + x[3] * x[3];
;         s += shx(s, 1, ln_); s += shx(s, 2, ln_); s += shx(s, 4, ln_); s += shx(s, 8, ln_);
;         if (g < c.nk_end) {
;           const float r2 = rsqrtf(s * (1.f / 64.f) + 1e-6f) * (g < 8 ? 0.125f * LOG2E : 1.f);
;           f32x4 gn = *(const f32x4*)(c.gain + (g < 8 ? 0 : 64) + (c4 & 63));
;           x = x * gn * r2;
;         }
;         *(u32x2*)(c.o16 + row * c.ldo + col) = MK2(pack2(x[0], x[1]), pack2(x[2], x[3]));
	v_fmaak_f32 v247, v250, v247, 0x358637bd
	v_rsq_f32_e32 v246, v246
	v_rsq_f32_e32 v247, v247
	s_nop 0
	v_mul_f32_e32 v246, v148, v246
	v_mul_f32_e32 v247, v148, v247
	v_fmaak_f32 v248, v250, v248, 0x358637bd
	v_fmaak_f32 v249, v250, v249, 0x358637bd
	v_rsq_f32_e32 v248, v248
	v_rsq_f32_e32 v249, v249
	s_nop 0
	v_mul_f32_e32 v248, v148, v248
	v_mul_f32_e32 v249, v148, v249
	v_pk_mul_f32 v[0:1], v[0:1], v[246:247]
	v_pk_mul_f32 v[2:3], v[2:3], v[248:249]
	v_pk_mul_f32 v[0:1], v[0:1], v[140:141] op_sel_hi:[1,0]
	v_pk_mul_f32 v[2:3], v[2:3], v[140:141] op_sel_hi:[1,0]
	v_pk_mul_f32 v[4:5], v[4:5], v[246:247]
	v_pk_mul_f32 v[6:7], v[6:7], v[248:249]
	v_pk_mul_f32 v[4:5], v[4:5], v[142:143] op_sel_hi:[1,0]
	v_pk_mul_f32 v[6:7], v[6:7], v[142:143] op_sel_hi:[1,0]
	v_pk_mul_f32 v[8:9], v[8:9], v[246:247]
	v_pk_mul_f32 v[10:11], v[10:11], v[248:249]
	v_pk_mul_f32 v[8:9], v[8:9], v[144:145] op_sel_hi:[1,0]
	v_pk_mul_f32 v[10:11], v[10:11], v[144:145] op_sel_hi:[1,0]
	v_pk_mul_f32 v[12:13], v[12:13], v[246:247]
	v_pk_mul_f32 v[14:15], v[14:15], v[248:249]
	v_pk_mul_f32 v[12:13], v[12:13], v[146:147] op_sel_hi:[1,0]
	v_pk_mul_f32 v[14:15], v[14:15], v[146:147] op_sel_hi:[1,0]
	v_mul_f32_e32 v246, v16, v16
	v_mul_f32_e32 v247, v17, v17
	v_mul_f32_e32 v248, v18, v18
	v_mul_f32_e32 v249, v19, v19
	v_fmac_f32_e32 v246, v20, v20
	v_fmac_f32_e32 v247, v21, v21
	v_fmac_f32_e32 v248, v22, v22
	v_fmac_f32_e32 v249, v23, v23
	v_fmac_f32_e32 v246, v24, v24
	v_fmac_f32_e32 v247, v25, v25
	v_fmac_f32_e32 v248, v26, v26
	v_fmac_f32_e32 v249, v27, v27
	v_fmac_f32_e32 v246, v28, v28
	v_fmac_f32_e32 v247, v29, v29
	v_fmac_f32_e32 v248, v30, v30
	v_fmac_f32_e32 v249, v31, v31
	v_add_f32_dpp v246, v246, v246 quad_perm:[1,0,3,2] row_mask:0xf bank_mask:0xf
	v_add_f32_dpp v247, v247, v247 quad_perm:[1,0,3,2] row_mask:0xf bank_mask:0xf
	v_add_f32_dpp v248, v248, v248 quad_perm:[1,0,3,2] row_mask:0xf bank_mask:0xf
	v_add_f32_dpp v249, v249, v249 quad_perm:[1,0,3,2] row_mask:0xf bank_mask:0xf
	v_add_f32_dpp v246, v246, v246 quad_perm:[2,3,0,1] row_mask:0xf bank_mask:0xf
	v_add_f32_dpp v247, v247, v247 quad_perm:[2,3,0,1] row_mask:0xf bank_mask:0xf
	v_add_f32_dpp v248, v248, v248 quad_perm:[2,3,0,1] row_mask:0xf bank_mask:0xf
	v_add_f32_dpp v249, v249, v249 quad_perm:[2,3,0,1] row_mask:0xf bank_mask:0xf
	v_add_f32_dpp v246, v246, v246 row_half_mirror row_mask:0xf bank_mask:0xf
	v_add_f32_dpp v247, v247, v247 row_half_mirror row_mask:0xf bank_mask:0xf
	v_add_f32_dpp v248, v248, v248 row_half_mirror row_mask:0xf bank_mask:0xf
	v_add_f32_dpp v249, v249, v249 row_half_mirror row_mask:0xf bank_mask:0xf
	v_add_f32_dpp v246, v246, v246 row_mirror row_mask:0xf bank_mask:0xf
	v_add_f32_dpp v247, v247, v247 row_mirror row_mask:0xf bank_mask:0xf
	v_add_f32_dpp v248, v248, v248 row_mirror row_mask:0xf bank_mask:0xf
	v_add_f32_dpp v249, v249, v249 row_mirror row_mask:0xf bank_mask:0xf
	v_fmaak_f32 v246, v250, v246, 0x358637bd
	v_fmaak_f32 v247, v250, v247, 0x358637bd
	v_rsq_f32_e32 v246, v246
	v_rsq_f32_e32 v247, v247
	s_nop 0
	v_mul_f32_e32 v246, v148, v246
	v_mul_f32_e32 v247, v148, v247
	v_fmaak_f32 v248, v250, v248, 0x358637bd
	v_fmaak_f32 v249, v250, v249, 0x358637bd
	v_rsq_f32_e32 v248, v248
	v_rsq_f32_e32 v249, v249
	s_nop 0
	v_mul_f32_e32 v248, v148, v248
	v_mul_f32_e32 v249, v148, v249
	v_pk_mul_f32 v[16:17], v[16:17], v[246:247]
	v_pk_mul_f32 v[18:19], v[18:19], v[248:249]
	v_pk_mul_f32 v[16:17], v[16:17], v[140:141] op_sel_hi:[1,0]
	v_pk_mul_f32 v[18:19], v[18:19], v[140:141] op_sel_hi:[1,0]
	v_pk_mul_f32 v[20:21], v[20:21], v[246:247]
	v_pk_mul_f32 v[22:23], v[22:23], v[248:249]
	v_pk_mul_f32 v[20:21], v[20:21], v[142:143] op_sel_hi:[1,0]
	v_pk_mul_f32 v[22:23], v[22:23], v[142:143] op_sel_hi:[1,0]
	v_pk_mul_f32 v[24:25], v[24:25], v[246:247]
	v_pk_mul_f32 v[26:27], v[26:27], v[248:249]
	v_pk_mul_f32 v[24:25], v[24:25], v[144:145] op_sel_hi:[1,0]
	v_pk_mul_f32 v[26:27], v[26:27], v[144:145] op_sel_hi:[1,0]
	v_pk_mul_f32 v[28:29], v[28:29], v[246:247]
	v_pk_mul_f32 v[30:31], v[30:31], v[248:249]
	v_pk_mul_f32 v[28:29], v[28:29], v[146:147] op_sel_hi:[1,0]
	v_pk_mul_f32 v[30:31], v[30:31], v[146:147] op_sel_hi:[1,0]
.Lqkv2_plain2:
	ds_write2_b32 v198, v0, v1 offset0:0 offset1:132
	ds_write2_b32 v199, v2, v3 offset0:0 offset1:132
	ds_write2_b32 v198, v4, v5 offset0:16 offset1:148
	ds_write2_b32 v199, v6, v7 offset0:16 offset1:148
	ds_write2_b32 v198, v8, v9 offset0:32 offset1:164
	ds_write2_b32 v199, v10, v11 offset0:32 offset1:164
	ds_write2_b32 v198, v12, v13 offset0:48 offset1:180
	ds_write2_b32 v199, v14, v15 offset0:48 offset1:180
	ds_write2_b32 v198, v16, v17 offset0:64 offset1:196
	ds_write2_b32 v199, v18, v19 offset0:64 offset1:196
	ds_write2_b32 v198, v20, v21 offset0:80 offset1:212
	ds_write2_b32 v199, v22, v23 offset0:80 offset1:212
	ds_write2_b32 v198, v24, v25 offset0:96 offset1:228
	ds_write2_b32 v199, v26, v27 offset0:96 offset1:228
	ds_write2_b32 v198, v28, v29 offset0:112 offset1:244
	ds_write2_b32 v199, v30, v31 offset0:112 offset1:244
	s_waitcnt lgkmcnt(0)
	ds_read_b128 v[0:3], v202
	ds_read_b128 v[4:7], v202 offset:1056
	ds_read_b128 v[8:11], v202 offset:2112
	ds_read_b128 v[12:15], v202 offset:3168
	ds_read_b128 v[16:19], v202 offset:4224
	ds_read_b128 v[20:23], v202 offset:5280
	ds_read_b128 v[24:27], v202 offset:6336
	ds_read_b128 v[28:31], v202 offset:7392
	s_waitcnt lgkmcnt(7)
	v_lshl_add_u64 v[206:207], v[204:205], 0, s[8:9]
	v_cvt_pk_bf16_f32 v0, v0, v1
	v_cvt_pk_bf16_f32 v1, v2, v3
	s_add_u32 s8, s8, s4
	s_addc_u32 s9, s9, 0
	global_store_dwordx2 v[206:207], v[0:1], off
	s_waitcnt lgkmcnt(6)
; DI float shx(float v, int mask, int lane) { return __int_as_float(__builtin_amdgcn_ds_bpermute((lane ^ mask) << 2, __float_as_int(v))); }
; DI void epi_slab(const GemmCfg c, const f32x16 (&acc)[4], float* sW, const float* rss, const size_t row0, const int g, const int lane,
;                  float* const g_h, u16* const g_hb, float* const g_out, const int final_out) {
;     ...
;       if (c.epi == EPI_QKV) {
;         f32x4 x = v * rs;
;         float s = x[0] * x[0] + x[1] * x[1] + x[2] * x[2] + x[3] * x[3];
;         s += shx(s, 1, ln_); s += shx(s, 2, ln_); s += shx(s, 4, ln_); s += shx(s, 8, ln_);
;         if (g < c.nk_end) {
;           const float r2 = rsqrtf(s * (1.f / 64.f) + 1e-6f) * (g < 8 ? 0.125f * LOG2E : 1.f);
;           f32x4 gn = *(const f32x4*)(c.gain + (g < 8 ? 0 : 64) + (c4 & 63));
;           x = x * gn * r2;
;         }
;         *(u32x2*)(c.o16 + row * c.ldo + col) = MK2(pack2(x[0], x[1]), pack2(x[2], x[3]));
	v_lshl_add_u64 v[206:207], v[204:205], 0, s[8:9]
	v_cvt_pk_bf16_f32 v4, v4, v5
	v_cvt_pk_bf16_f32 v5, v6, v7
	s_add_u32 s8, s8, s4
	s_addc_u32 s9, s9, 0
	global_store_dwordx2 v[206:207], v[4:5], off
	s_waitcnt lgkmcnt(5)
	v_lshl_add_u64 v[206:207], v[204:205], 0, s[8:9]
	v_cvt_pk_bf16_f32 v8, v8, v9
	v_cvt_pk_bf16_f32 v9, v10, v11
	s_add_u32 s8, s8, s4
	s_addc_u32 s9, s9, 0
	global_store_dwordx2 v[206:207], v[8:9], off
	s_waitcnt lgkmcnt(4)
	v_lshl_add_u64 v[206:207], v[204:205], 0, s[8:9]
	v_cvt_pk_bf16_f32 v12, v12, v13
	v_cvt_pk_bf16_f32 v13, v14, v15
	s_add_u32 s8, s8, s4
	s_addc_u32 s9, s9, 0
	global_store_dwordx2 v[206:207], v[12:13], off
	s_waitcnt lgkmcnt(3)
	v_lshl_add_u64 v[206:207], v[204:205], 0, s[8:9]
	v_cvt_pk_bf16_f32 v16, v16, v17
	v_cvt_pk_bf16_f32 v17, v18, v19
	s_add_u32 s8, s8, s4
	s_addc_u32 s9, s9, 0
	global_store_dwordx2 v[206:207], v[16:17], off
	s_waitcnt lgkmcnt(2)
	v_lshl_add_u64 v[206:207], v[204:205], 0, s[8:9]
	v_cvt_pk_bf16_f32 v20, v20, v21
	v_cvt_pk_bf16_f32 v21, v22, v23
	s_add_u32 s8, s8, s4
	s_addc_u32 s9, s9, 0
	global_store_dwordx2 v[206:207], v[20:21], off
	s_waitcnt lgkmcnt(1)
	v_lshl_add_u64 v[206:207], v[204:205], 0, s[8:9]
	v_cvt_pk_bf16_f32 v24, v24, v25
	v_cvt_pk_bf16_f32 v25, v26, v27
	s_add_u32 s8, s8, s4
	s_addc_u32 s9, s9, 0
	global_store_dwordx2 v[206:207], v[24:25], off
	s_waitcnt lgkmcnt(0)
	v_lshl_add_u64 v[206:207], v[204:205], 0, s[8:9]
	v_cvt_pk_bf16_f32 v28, v28, v29
	v_cvt_pk_bf16_f32 v29, v30, v31
	s_add_u32 s8, s8, s4
	s_addc_u32 s9, s9, 0
	global_store_dwordx2 v[206:207], v[28:29], off
	v_pk_mul_f32 v[32:33], v[32:33], v[238:239]
	v_pk_mul_f32 v[34:35], v[34:35], v[240:241]
	v_pk_mul_f32 v[36:37], v[36:37], v[238:239]
	v_pk_mul_f32 v[38:39], v[38:39], v[240:241]
	v_pk_mul_f32 v[40:41], v[40:41], v[238:239]
	v_pk_mul_f32 v[42:43], v[42:43], v[240:241]
	v_pk_mul_f32 v[44:45], v[44:45], v[238:239]
	v_pk_mul_f32 v[46:47], v[46:47], v[240:241]
	v_pk_mul_f32 v[48:49], v[48:49], v[238:239]
	v_pk_mul_f32 v[50:51], v[50:51], v[240:241]
	v_pk_mul_f32 v[52:53], v[52:53], v[238:239]
	v_pk_mul_f32 v[54:55], v[54:55], v[240:241]
	v_pk_mul_f32 v[56:57], v[56:57], v[238:239]
	v_pk_mul_f32 v[58:59], v[58:59], v[240:241]
	v_pk_mul_f32 v[60:61], v[60:61], v[238:239]
	v_pk_mul_f32 v[62:63], v[62:63], v[240:241]
	s_and_b64 vcc, exec, s[72:73]
	s_cbranch_vccz .Lqkv2_plain3
	v_mul_f32_e32 v246, v32, v32
	v_mul_f32_e32 v247, v33, v33
	v_mul_f32_e32 v248, v34, v34
	v_mul_f32_e32 v249, v35, v35
	v_fmac_f32_e32 v246, v36, v36
	v_fmac_f32_e32 v247, v37, v37
	v_fmac_f32_e32 v248, v38, v38
	v_fmac_f32_e32 v249, v39, v39
	v_fmac_f32_e32 v246, v40, v40
	v_fmac_f32_e32 v247, v41, v41
	v_fmac_f32_e32 v248, v42, v42
	v_fmac_f32_e32 v249, v43, v43
	v_fmac_f32_e32 v246, v44, v44
	v_fmac_f32_e32 v247, v45, v45
	v_fmac_f32_e32 v248, v46, v46
	v_fmac_f32_e32 v249, v47, v47
	v_add_f32_dpp v246, v246, v246 quad_perm:[1,0,3,2] row_mask:0xf bank_mask:0xf
	v_add_f32_dpp v247, v247, v247 quad_perm:[1,0,3,2] row_mask:0xf bank_mask:0xf
	v_add_f32_dpp v248, v248, v248 quad_perm:[1,0,3,2] row_mask:0xf bank_mask:0xf
	v_add_f32_dpp v249, v249, v249 quad_perm:[1,0,3,2] row_mask:0xf bank_mask:0xf
	v_add_f32_dpp v246, v246, v246 quad_perm:[2,3,0,1] row_mask:0xf bank_mask:0xf
	v_add_f32_dpp v247, v247, v247 quad_perm:[2,3,0,1] row_mask:0xf bank_mask:0xf
	v_add_f32_dpp v248, v248, v248 quad_perm:[2,3,0,1] row_mask:0xf bank_mask:0xf
	v_add_f32_dpp v249, v249, v249 quad_perm:[2,3,0,1] row_mask:0xf bank_mask:0xf
	v_add_f32_dpp v246, v246, v246 row_half_mirror row_mask:0xf bank_mask:0xf
	v_add_f32_dpp v247, v247, v247 row_half_mirror row_mask:0xf bank_mask:0xf
	v_add_f32_dpp v248, v248, v248 row_half_mirror row_mask:0xf bank_mask:0xf
	v_add_f32_dpp v249, v249, v249 row_half_mirror row_mask:0xf bank_mask:0xf
	v_add_f32_dpp v246, v246, v246 row_mirror row_mask:0xf bank_mask:0xf
	v_add_f32_dpp v247, v247, v247 row_mirror row_mask:0xf bank_mask:0xf
	v_add_f32_dpp v248, v248, v248 row_mirror row_mask:0xf bank_mask:0xf
	v_add_f32_dpp v249, v249, v249 row_mirror row_mask:0xf bank_mask:0xf
	v_fmaak_f32 v246, v250, v246, 0x358637bd
	v_fmaak_f32 v247, v250, v247, 0x358637bd
	v_rsq_f32_e32 v246, v246
	v_rsq_f32_e32 v247, v247
	s_nop 0
	v_mul_f32_e32 v246, v148, v246
	v_mul_f32_e32 v247, v148, v247
	v_fmaak_f32 v248, v250, v248, 0x358637bd
	v_fmaak_f32 v249, v250, v249, 0x358637bd
	v_rsq_f32_e32 v248, v248
	v_rsq_f32_e32 v249, v249
	s_nop 0
	v_mul_f32_e32 v248, v148, v248
	v_mul_f32_e32 v249, v148, v249
	v_pk_mul_f32 v[32:33], v[32:33], v[246:247]
	v_pk_mul_f32 v[34:35], v[34:35], v[248:249]
	v_pk_mul_f32 v[32:33], v[32:33], v[140:141] op_sel_hi:[1,0]
	v_pk_mul_f32 v[34:35], v[34:35], v[140:141] op_sel_hi:[1,0]
	v_pk_mul_f32 v[36:37], v[36:37], v[246:247]
	v_pk_mul_f32 v[38:39], v[38:39], v[248:249]
	v_pk_mul_f32 v[36:37], v[36:37], v[142:143] op_sel_hi:[1,0]
	v_pk_mul_f32 v[38:39], v[38:39], v[142:143] op_sel_hi:[1,0]
	v_pk_mul_f32 v[40:41], v[40:41], v[246:247]
	v_pk_mul_f32 v[42:43], v[42:43], v[248:249]
	v_pk_mul_f32 v[40:41], v[40:41], v[144:145] op_sel_hi:[1,0]
	v_pk_mul_f32 v[42:43], v[42:43], v[144:145] op_sel_hi:[1,0]
	v_pk_mul_f32 v[44:45], v[44:45], v[246:247]
	v_pk_mul_f32 v[46:47], v[46:47], v[248:249]
	v_pk_mul_f32 v[44:45], v[44:45], v[146:147] op_sel_hi:[1,0]
	v_pk_mul_f32 v[46:47], v[46:47], v[146:147] op_sel_hi:[1,0]
	v_mul_f32_e32 v246, v48, v48
	v_mul_f32_e32 v247, v49, v49
	v_mul_f32_e32 v248, v50, v50
	v_mul_f32_e32 v249, v51, v51
	v_fmac_f32_e32 v246, v52, v52
	v_fmac_f32_e32 v247, v53, v53
	v_fmac_f32_e32 v248, v54, v54
	v_fmac_f32_e32 v249, v55, v55
	v_fmac_f32_e32 v246, v56, v56
	v_fmac_f32_e32 v247, v57, v57
; DI float shx(float v, int mask, int lane) { return __int_as_float(__builtin_amdgcn_ds_bpermute((lane ^ mask) << 2, __float_as_int(v))); }
; DI int crow(int i, int hh) { return (i & 3) + 8 * (i >> 2) + 4 * hh; }
; DI void epi_slab(const GemmCfg c, const f32x16 (&acc)[4], float* sW, const float* rss, const size_t row0, const int g, const int lane,
;                  float* const g_h, u16* const g_hb, float* const g_out, const int final_out) {
;     ...
;   for (int nb = 0; nb < 4; ++nb)
; #pragma unroll
;     for (int i = 0; i < 16; ++i) sW[crow(i, hh) * 132 + nb * 32 + l31] = acc[nb][i];
;     ...
;       if (c.epi == EPI_QKV) {
;         f32x4 x = v * rs;
;         float s = x[0] * x[0] + x[1] * x[1] + x[2] * x[2] + x[3] * x[3];
;         s += shx(s, 1, ln_); s += shx(s, 2, ln_); s += shx(s, 4, ln_); s += shx(s, 8, ln_);
;         if (g < c.nk_end) {
;           const float r2 = rsqrtf(s * (1.f / 64.f) + 1e-6f) * (g < 8 ? 0.125f * LOG2E : 1.f);
;           f32x4 gn = *(const f32x4*)(c.gain + (g < 8 ? 0 : 64) + (c4 & 63));
;           x = x * gn * r2;
;         }
;         *(u32x2*)(c.o16 + row * c.ldo + col) = MK2(pack2(x[0], x[1]), pack2(x[2], x[3]));
	v_fmac_f32_e32 v248, v58, v58
	v_fmac_f32_e32 v249, v59, v59
	v_fmac_f32_e32 v246, v60, v60
	v_fmac_f32_e32 v247, v61, v61
	v_fmac_f32_e32 v248, v62, v62
	v_fmac_f32_e32 v249, v63, v63
	v_add_f32_dpp v246, v246, v246 quad_perm:[1,0,3,2] row_mask:0xf bank_mask:0xf
	v_add_f32_dpp v247, v247, v247 quad_perm:[1,0,3,2] row_mask:0xf bank_mask:0xf
	v_add_f32_dpp v248, v248, v248 quad_perm:[1,0,3,2] row_mask:0xf bank_mask:0xf
	v_add_f32_dpp v249, v249, v249 quad_perm:[1,0,3,2] row_mask:0xf bank_mask:0xf
	v_add_f32_dpp v246, v246, v246 quad_perm:[2,3,0,1] row_mask:0xf bank_mask:0xf
	v_add_f32_dpp v247, v247, v247 quad_perm:[2,3,0,1] row_mask:0xf bank_mask:0xf
	v_add_f32_dpp v248, v248, v248 quad_perm:[2,3,0,1] row_mask:0xf bank_mask:0xf
	v_add_f32_dpp v249, v249, v249 quad_perm:[2,3,0,1] row_mask:0xf bank_mask:0xf
	v_add_f32_dpp v246, v246, v246 row_half_mirror row_mask:0xf bank_mask:0xf
	v_add_f32_dpp v247, v247, v247 row_half_mirror row_mask:0xf bank_mask:0xf
	v_add_f32_dpp v248, v248, v248 row_half_mirror row_mask:0xf bank_mask:0xf
	v_add_f32_dpp v249, v249, v249 row_half_mirror row_mask:0xf bank_mask:0xf
	v_add_f32_dpp v246, v246, v246 row_mirror row_mask:0xf bank_mask:0xf
	v_add_f32_dpp v247, v247, v247 row_mirror row_mask:0xf bank_mask:0xf
	v_add_f32_dpp v248, v248, v248 row_mirror row_mask:0xf bank_mask:0xf
	v_add_f32_dpp v249, v249, v249 row_mirror row_mask:0xf bank_mask:0xf
	v_fmaak_f32 v246, v250, v246, 0x358637bd
	v_fmaak_f32 v247, v250, v247, 0x358637bd
	v_rsq_f32_e32 v246, v246
	v_rsq_f32_e32 v247, v247
	s_nop 0
	v_mul_f32_e32 v246, v148, v246
	v_mul_f32_e32 v247, v148, v247
	v_fmaak_f32 v248, v250, v248, 0x358637bd
	v_fmaak_f32 v249, v250, v249, 0x358637bd
	v_rsq_f32_e32 v248, v248
	v_rsq_f32_e32 v249, v249
	s_nop 0
	v_mul_f32_e32 v248, v148, v248
	v_mul_f32_e32 v249, v148, v249
	v_pk_mul_f32 v[48:49], v[48:49], v[246:247]
	v_pk_mul_f32 v[50:51], v[50:51], v[248:249]
	v_pk_mul_f32 v[48:49], v[48:49], v[140:141] op_sel_hi:[1,0]
	v_pk_mul_f32 v[50:51], v[50:51], v[140:141] op_sel_hi:[1,0]
	v_pk_mul_f32 v[52:53], v[52:53], v[246:247]
	v_pk_mul_f32 v[54:55], v[54:55], v[248:249]
	v_pk_mul_f32 v[52:53], v[52:53], v[142:143] op_sel_hi:[1,0]
	v_pk_mul_f32 v[54:55], v[54:55], v[142:143] op_sel_hi:[1,0]
	v_pk_mul_f32 v[56:57], v[56:57], v[246:247]
	v_pk_mul_f32 v[58:59], v[58:59], v[248:249]
	v_pk_mul_f32 v[56:57], v[56:57], v[144:145] op_sel_hi:[1,0]
	v_pk_mul_f32 v[58:59], v[58:59], v[144:145] op_sel_hi:[1,0]
	v_pk_mul_f32 v[60:61], v[60:61], v[246:247]
	v_pk_mul_f32 v[62:63], v[62:63], v[248:249]
	v_pk_mul_f32 v[60:61], v[60:61], v[146:147] op_sel_hi:[1,0]
	v_pk_mul_f32 v[62:63], v[62:63], v[146:147] op_sel_hi:[1,0]
.Lqkv2_plain3:
	ds_write2_b32 v198, v32, v33 offset0:0 offset1:132
	ds_write2_b32 v199, v34, v35 offset0:0 offset1:132
	ds_write2_b32 v198, v36, v37 offset0:16 offset1:148
	ds_write2_b32 v199, v38, v39 offset0:16 offset1:148
	ds_write2_b32 v198, v40, v41 offset0:32 offset1:164
	ds_write2_b32 v199, v42, v43 offset0:32 offset1:164
	ds_write2_b32 v198, v44, v45 offset0:48 offset1:180
	ds_write2_b32 v199, v46, v47 offset0:48 offset1:180
	ds_write2_b32 v198, v48, v49 offset0:64 offset1:196
	ds_write2_b32 v199, v50, v51 offset0:64 offset1:196
	ds_write2_b32 v198, v52, v53 offset0:80 offset1:212
	ds_write2_b32 v199, v54, v55 offset0:80 offset1:212
	ds_write2_b32 v198, v56, v57 offset0:96 offset1:228
	ds_write2_b32 v199, v58, v59 offset0:96 offset1:228
	ds_write2_b32 v198, v60, v61 offset0:112 offset1:244
	ds_write2_b32 v199, v62, v63 offset0:112 offset1:244
	s_waitcnt lgkmcnt(0)
	ds_read_b128 v[32:35], v202
	ds_read_b128 v[36:39], v202 offset:1056
	ds_read_b128 v[40:43], v202 offset:2112
	ds_read_b128 v[44:47], v202 offset:3168
	ds_read_b128 v[48:51], v202 offset:4224
	ds_read_b128 v[52:55], v202 offset:5280
	ds_read_b128 v[56:59], v202 offset:6336
	ds_read_b128 v[60:63], v202 offset:7392
	s_waitcnt lgkmcnt(7)
	v_lshl_add_u64 v[206:207], v[204:205], 0, s[8:9]
	v_cvt_pk_bf16_f32 v32, v32, v33
	v_cvt_pk_bf16_f32 v33, v34, v35
	s_add_u32 s8, s8, s4
	s_addc_u32 s9, s9, 0
	global_store_dwordx2 v[206:207], v[32:33], off
	s_waitcnt lgkmcnt(6)
	v_lshl_add_u64 v[206:207], v[204:205], 0, s[8:9]
	v_cvt_pk_bf16_f32 v36, v36, v37
	v_cvt_pk_bf16_f32 v37, v38, v39
	s_add_u32 s8, s8, s4
	s_addc_u32 s9, s9, 0
	global_store_dwordx2 v[206:207], v[36:37], off
	s_waitcnt lgkmcnt(5)
	v_lshl_add_u64 v[206:207], v[204:205], 0, s[8:9]
	v_cvt_pk_bf16_f32 v40, v40, v41
	v_cvt_pk_bf16_f32 v41, v42, v43
	s_add_u32 s8, s8, s4
	s_addc_u32 s9, s9, 0
	global_store_dwordx2 v[206:207], v[40:41], off
	s_waitcnt lgkmcnt(4)
	v_lshl_add_u64 v[206:207], v[204:205], 0, s[8:9]
	v_cvt_pk_bf16_f32 v44, v44, v45
	v_cvt_pk_bf16_f32 v45, v46, v47
	s_add_u32 s8, s8, s4
	s_addc_u32 s9, s9, 0
	global_store_dwordx2 v[206:207], v[44:45], off
	s_waitcnt lgkmcnt(3)
	v_lshl_add_u64 v[206:207], v[204:205], 0, s[8:9]
	v_cvt_pk_bf16_f32 v48, v48, v49
	v_cvt_pk_bf16_f32 v49, v50, v51
	s_add_u32 s8, s8, s4
	s_addc_u32 s9, s9, 0
	global_store_dwordx2 v[206:207], v[48:49], off
	s_waitcnt lgkmcnt(2)
	v_lshl_add_u64 v[206:207], v[204:205], 0, s[8:9]
	v_cvt_pk_bf16_f32 v52, v52, v53
	v_cvt_pk_bf16_f32 v53, v54, v55
	s_add_u32 s8, s8, s4
	s_addc_u32 s9, s9, 0
	global_store_dwordx2 v[206:207], v[52:53], off
	s_waitcnt lgkmcnt(1)
	v_lshl_add_u64 v[206:207], v[204:205], 0, s[8:9]
	v_cvt_pk_bf16_f32 v56, v56, v57
	v_cvt_pk_bf16_f32 v57, v58, v59
	s_add_u32 s8, s8, s4
	s_addc_u32 s9, s9, 0
	global_store_dwordx2 v[206:207], v[56:57], off
	s_waitcnt lgkmcnt(0)
	v_lshl_add_u64 v[206:207], v[204:205], 0, s[8:9]
	v_cvt_pk_bf16_f32 v60, v60, v61
	v_cvt_pk_bf16_f32 v61, v62, v63
	s_add_u32 s8, s8, s4
	s_addc_u32 s9, s9, 0
	global_store_dwordx2 v[206:207], v[60:61], off
	s_branch .LBB0_108
; DI float shx(float v, int mask, int lane) { return __int_as_float(__builtin_amdgcn_ds_bpermute((lane ^ mask) << 2, __float_as_int(v))); }
; DI void epi_slab(const GemmCfg c, const f32x16 (&acc)[4], float* sW, const float* rss, const size_t row0, const int g, const int lane,
;                  float* const g_h, u16* const g_hb, float* const g_out, const int final_out) {
;     ...
;       } else if (c.epi == EPI_QABS) {
;         f32x4 x = v * rs;
;         float s = x[0] * x[0] + x[1] * x[1] + x[2] * x[2] + x[3] * x[3];
;         s += shx(s, 1, ln_); s += shx(s, 2, ln_); s += shx(s, 4, ln_); s += shx(s, 8, ln_); s += shx(s, 16, ln_);
;         if (l31 == 0) c.f0[row * 32 + g] = s;
;         *(u32x2*)(c.o16 + row * 4096 + col) = MK2(pack2(x[0], x[1]), pack2(x[2], x[3]));
; DI void gemm_run(const GemmCfg c, char* smem, float* const g_h, u16* const g_hb, float* const g_out, const int final_out) {
;     ...
;   for (int slot = Lb; slot < ntiles; slot += G) {
;     const int sr = slot / srow, idx = slot - sr * srow;
;     const int tm = sr < 8 ? sr * 8 + (idx & 7) : 64;
;     const int tn = sr < 8 ? (idx >> 3) : idx;
;     const u16* Ag = c.A + (size_t)(tm * 256 + lrow) * c.lda + tn * c.a_koff_tn + lch * 8;
;     const u16* Bg = c.Bt + (size_t)(tn * 256 + lrow) * K + lch * 8;
;     const size_t astep = (size_t)64 * c.lda, bstep = (size_t)64 * K;
.Lqabs2:
	v_and_b32_e32 v222, 15, v185
	v_lshrrev_b32_e32 v223, 4, v185
	s_lshl_b32 s4, s86, 2
	s_add_i32 s4, s4, 0x24000
	v_lshl_add_u32 v224, v223, 4, s4
	ds_read_b128 v[226:229], v224
	ds_read_b128 v[230:233], v224 offset:64
	ds_read_b128 v[234:237], v224 offset:128
	ds_read_b128 v[238:241], v224 offset:192
	s_lshr_b32 s4, s86, 5
	s_or_b32 s4, s4, s75
	s_and_b32 s5, s4, 3
	s_mul_i32 s5, s5, 0x2400
	s_cmp_lt_u32 s4, 4
	s_mov_b32 s4, 0x1b000
	s_cselect_b32 s4, 0x9000, s4
	s_add_i32 s4, s4, s5
	v_mul_u32_u24_e32 v198, 0x840, v223
	v_lshl_add_u32 v198, v222, 2, v198
	v_add_u32_e32 v198, s4, v198
	v_add_u32_e32 v199, 0x420, v198
	v_lshrrev_b32_e32 v202, 5, v185
	v_and_b32_e32 v206, 31, v185
	v_mul_u32_u24_e32 v204, 0x210, v202
	v_lshl_add_u32 v204, v206, 4, v204
	v_add_u32_e32 v250, s4, v204
	v_add_u32_e32 v204, s6, v202
	v_lshlrev_b32_e32 v204, 13, v204
	v_lshl_add_u32 v206, v206, 2, s64
	v_lshl_add_u32 v204, v206, 1, v204
	v_mov_b32_e32 v205, 0
	v_lshl_add_u64 v[204:205], v[204:205], 0, s[56:57]
	v_mov_b32_e32 v202, v250
	v_mov_b32_e32 v250, 0x3c800000
	v_lshl_add_u32 v242, v223, 2, s6
	v_lshlrev_b32_e32 v242, 7, v242
	s_lshr_b32 s5, s64, 5
	v_add_u32_e32 v242, s5, v242
	v_mov_b32_e32 v243, 0
	v_lshl_add_u64 v[242:243], v[242:243], 0, s[76:77]
	v_mov_b32_e32 v244, 0x800
	v_mov_b32_e32 v245, 0
	v_readlane_b32 s6, v254, 26
	s_mov_b32 s9, 0
	s_nop 0
	s_add_i32 s7, s48, s6
	s_cmp_ge_i32 s7, s74
	s_cbranch_scc1 .Lqabs2_nopf
	s_abs_i32 s1, s7
	s_mul_hi_u32 s4, s1, s69
	s_mul_i32 s5, s4, s30
	s_ashr_i32 s0, s7, 31
	s_sub_i32 s1, s1, s5
	s_xor_b32 s0, s0, s63
	s_add_i32 s5, s4, 1
	s_sub_i32 s6, s1, s30
	s_cmp_ge_u32 s1, s30
	s_cselect_b32 s4, s5, s4
	s_cselect_b32 s1, s6, s1
	s_add_i32 s5, s4, 1
	s_cmp_ge_u32 s1, s30
	s_cselect_b32 s1, s5, s4
	s_xor_b32 s1, s1, s0
	s_sub_i32 s0, s1, s0
	s_mul_i32 s1, s0, s65
	s_sub_i32 s1, s7, s1
	s_lshl_b32 s4, s0, 3
	s_and_b32 s5, s7, 7
	s_or_b32 s4, s4, s5
	s_ashr_i32 s5, s1, 3
	s_cmp_lt_i32 s0, 8
	s_cselect_b32 s78, s4, 64
	s_cselect_b32 s49, s5, s1
	v_lshrrev_b32_e32 v128, 3, v185
	v_and_b32_e32 v129, 7, v185
	v_xor_b32_e32 v129, v129, v128
	v_lshlrev_b32_e32 v129, 4, v129
	s_lshl_b32 s0, s62, 1
	v_mul_lo_u32 v130, v128, s0
	s_lshl_b32 s1, s62, 4
	v_add_u32_e32 v130, v130, v129
	v_add_u32_e32 v131, s1, v130
	v_add_u32_e32 v132, s1, v131
	v_add_u32_e32 v133, s1, v132
	s_lshl_b32 s0, s60, 1
	v_mul_lo_u32 v134, v128, s0
	s_lshl_b32 s1, s60, 4
	v_add_u32_e32 v134, v134, v129
	v_add_u32_e32 v135, s1, v134
	v_add_u32_e32 v136, s1, v135
	v_add_u32_e32 v137, s1, v136
	s_lshl_b32 s8, s75, 5
	s_add_i32 s8, s8, s86
	s_lshl_b32 s0, s78, 8
	s_add_i32 s0, s0, s8
	s_mul_i32 s0, s0, s62
	s_mul_i32 s1, s49, s2
	s_add_i32 s0, s0, s1
	s_lshl_b32 s0, s0, 1
	s_add_u32 s4, s54, s0
	s_addc_u32 s5, s55, 0
	v_readlane_b32 s6, v255, 5
	v_readlane_b32 s7, v255, 6
	s_lshl_b32 s0, s49, 8
	s_add_i32 s0, s0, s8
	s_mul_i32 s0, s0, s60
	s_lshl_b32 s0, s0, 1
	s_add_u32 s6, s6, s0
	s_addc_u32 s7, s7, 0
	s_lshl_b32 s8, s8, 7
	s_add_u32 m0, s8, 0x0
	s_nop 0
	global_load_lds_dwordx4 v130, s[4:5]
	s_add_u32 m0, s8, 0x12000
	s_nop 0
	global_load_lds_dwordx4 v134, s[6:7]
	s_add_u32 m0, s8, 0x400
	s_nop 0
	global_load_lds_dwordx4 v131, s[4:5]
	s_add_u32 m0, s8, 0x12400
	s_nop 0
	global_load_lds_dwordx4 v135, s[6:7]
	s_add_u32 m0, s8, 0x800
	s_nop 0
	global_load_lds_dwordx4 v132, s[4:5]
	s_add_u32 m0, s8, 0x12800
	s_nop 0
	global_load_lds_dwordx4 v136, s[6:7]
	s_add_u32 m0, s8, 0xc00
	s_nop 0
	global_load_lds_dwordx4 v133, s[4:5]
	s_add_u32 m0, s8, 0x12c00
	s_nop 0
	global_load_lds_dwordx4 v137, s[6:7]
	s_mov_b32 s9, 1
.Lqabs2_nopf:
	s_nop 0
	v_writelane_b32 v255, s9, 51
	s_movk_i32 s4, 0x4000
	s_mov_b64 s[8:9], 0
	s_waitcnt lgkmcnt(0)
	v_fmaak_f32 v226, v191, v226, 0x358637bd
	v_fmaak_f32 v227, v191, v227, 0x358637bd
	v_rsq_f32_e32 v226, v226
	v_rsq_f32_e32 v227, v227
	s_nop 0
	v_fmaak_f32 v228, v191, v228, 0x358637bd
	v_fmaak_f32 v229, v191, v229, 0x358637bd
	v_rsq_f32_e32 v228, v228
	v_rsq_f32_e32 v229, v229
	s_nop 0
	v_fmaak_f32 v230, v191, v230, 0x358637bd
	v_fmaak_f32 v231, v191, v231, 0x358637bd
	v_rsq_f32_e32 v230, v230
	v_rsq_f32_e32 v231, v231
	s_nop 0
	v_fmaak_f32 v232, v191, v232, 0x358637bd
	v_fmaak_f32 v233, v191, v233, 0x358637bd
	v_rsq_f32_e32 v232, v232
	v_rsq_f32_e32 v233, v233
	s_nop 0
	v_fmaak_f32 v234, v191, v234, 0x358637bd
	v_fmaak_f32 v235, v191, v235, 0x358637bd
	v_rsq_f32_e32 v234, v234
	v_rsq_f32_e32 v235, v235
	s_nop 0
	v_fmaak_f32 v236, v191, v236, 0x358637bd
	v_fmaak_f32 v237, v191, v237, 0x358637bd
	v_rsq_f32_e32 v236, v236
	v_rsq_f32_e32 v237, v237
	s_nop 0
	v_fmaak_f32 v238, v191, v238, 0x358637bd
	v_fmaak_f32 v239, v191, v239, 0x358637bd
	v_rsq_f32_e32 v238, v238
	v_rsq_f32_e32 v239, v239
	s_nop 0
	v_fmaak_f32 v240, v191, v240, 0x358637bd
	v_fmaak_f32 v241, v191, v241, 0x358637bd
	v_rsq_f32_e32 v240, v240
	v_rsq_f32_e32 v241, v241
	s_nop 0
	v_pk_mul_f32 v[64:65], v[64:65], v[226:227]
	v_pk_mul_f32 v[66:67], v[66:67], v[228:229]
	v_pk_mul_f32 v[68:69], v[68:69], v[226:227]
	v_pk_mul_f32 v[70:71], v[70:71], v[228:229]
	v_pk_mul_f32 v[72:73], v[72:73], v[226:227]
	v_pk_mul_f32 v[74:75], v[74:75], v[228:229]
	v_pk_mul_f32 v[76:77], v[76:77], v[226:227]
	v_pk_mul_f32 v[78:79], v[78:79], v[228:229]
	v_pk_mul_f32 v[80:81], v[80:81], v[226:227]
	v_pk_mul_f32 v[82:83], v[82:83], v[228:229]
	v_pk_mul_f32 v[84:85], v[84:85], v[226:227]
	v_pk_mul_f32 v[86:87], v[86:87], v[228:229]
	v_pk_mul_f32 v[88:89], v[88:89], v[226:227]
	v_pk_mul_f32 v[90:91], v[90:91], v[228:229]
	v_pk_mul_f32 v[92:93], v[92:93], v[226:227]
	v_pk_mul_f32 v[94:95], v[94:95], v[228:229]
	v_mul_f32_e32 v246, v64, v64
	v_mul_f32_e32 v247, v65, v65
; DI float shx(float v, int mask, int lane) { return __int_as_float(__builtin_amdgcn_ds_bpermute((lane ^ mask) << 2, __float_as_int(v))); }
; DI void epi_slab(const GemmCfg c, const f32x16 (&acc)[4], float* sW, const float* rss, const size_t row0, const int g, const int lane,
;                  float* const g_h, u16* const g_hb, float* const g_out, const int final_out) {
;     ...
;       } else if (c.epi == EPI_QABS) {
;         f32x4 x = v * rs;
;         float s = x[0] * x[0] + x[1] * x[1] + x[2] * x[2] + x[3] * x[3];
;         s += shx(s, 1, ln_); s += shx(s, 2, ln_); s += shx(s, 4, ln_); s += shx(s, 8, ln_); s += shx(s, 16, ln_);
;         if (l31 == 0) c.f0[row * 32 + g] = s;
;         *(u32x2*)(c.o16 + row * 4096 + col) = MK2(pack2(x[0], x[1]), pack2(x[2], x[3]));
	v_mul_f32_e32 v248, v66, v66
	v_mul_f32_e32 v249, v67, v67
	v_fmac_f32_e32 v246, v68, v68
	v_fmac_f32_e32 v247, v69, v69
	v_fmac_f32_e32 v248, v70, v70
	v_fmac_f32_e32 v249, v71, v71
	v_fmac_f32_e32 v246, v72, v72
	v_fmac_f32_e32 v247, v73, v73
	v_fmac_f32_e32 v248, v74, v74
	v_fmac_f32_e32 v249, v75, v75
	v_fmac_f32_e32 v246, v76, v76
	v_fmac_f32_e32 v247, v77, v77
	v_fmac_f32_e32 v248, v78, v78
	v_fmac_f32_e32 v249, v79, v79
	v_fmac_f32_e32 v246, v80, v80
	v_fmac_f32_e32 v247, v81, v81
	v_fmac_f32_e32 v248, v82, v82
	v_fmac_f32_e32 v249, v83, v83
	v_fmac_f32_e32 v246, v84, v84
	v_fmac_f32_e32 v247, v85, v85
	v_fmac_f32_e32 v248, v86, v86
	v_fmac_f32_e32 v249, v87, v87
	v_fmac_f32_e32 v246, v88, v88
	v_fmac_f32_e32 v247, v89, v89
	v_fmac_f32_e32 v248, v90, v90
	v_fmac_f32_e32 v249, v91, v91
	v_fmac_f32_e32 v246, v92, v92
	v_fmac_f32_e32 v247, v93, v93
	v_fmac_f32_e32 v248, v94, v94
	v_fmac_f32_e32 v249, v95, v95
	v_add_f32_dpp v246, v246, v246 quad_perm:[1,0,3,2] row_mask:0xf bank_mask:0xf
	v_add_f32_dpp v247, v247, v247 quad_perm:[1,0,3,2] row_mask:0xf bank_mask:0xf
	v_add_f32_dpp v248, v248, v248 quad_perm:[1,0,3,2] row_mask:0xf bank_mask:0xf
	v_add_f32_dpp v249, v249, v249 quad_perm:[1,0,3,2] row_mask:0xf bank_mask:0xf
	v_add_f32_dpp v246, v246, v246 quad_perm:[2,3,0,1] row_mask:0xf bank_mask:0xf
	v_add_f32_dpp v247, v247, v247 quad_perm:[2,3,0,1] row_mask:0xf bank_mask:0xf
	v_add_f32_dpp v248, v248, v248 quad_perm:[2,3,0,1] row_mask:0xf bank_mask:0xf
	v_add_f32_dpp v249, v249, v249 quad_perm:[2,3,0,1] row_mask:0xf bank_mask:0xf
	v_add_f32_dpp v246, v246, v246 row_half_mirror row_mask:0xf bank_mask:0xf
	v_add_f32_dpp v247, v247, v247 row_half_mirror row_mask:0xf bank_mask:0xf
	v_add_f32_dpp v248, v248, v248 row_half_mirror row_mask:0xf bank_mask:0xf
	v_add_f32_dpp v249, v249, v249 row_half_mirror row_mask:0xf bank_mask:0xf
	v_add_f32_dpp v246, v246, v246 row_mirror row_mask:0xf bank_mask:0xf
	v_add_f32_dpp v247, v247, v247 row_mirror row_mask:0xf bank_mask:0xf
	v_add_f32_dpp v248, v248, v248 row_mirror row_mask:0xf bank_mask:0xf
	v_add_f32_dpp v249, v249, v249 row_mirror row_mask:0xf bank_mask:0xf
	global_store_dword v[242:243], v246, off offset:0
	global_store_dword v[242:243], v247, off offset:128
	global_store_dword v[242:243], v248, off offset:256
	global_store_dword v[242:243], v249, off offset:384
	ds_write2_b32 v198, v64, v65 offset0:0 offset1:132
	ds_write2_b32 v199, v66, v67 offset0:0 offset1:132
	ds_write2_b32 v198, v68, v69 offset0:16 offset1:148
	ds_write2_b32 v199, v70, v71 offset0:16 offset1:148
	ds_write2_b32 v198, v72, v73 offset0:32 offset1:164
	ds_write2_b32 v199, v74, v75 offset0:32 offset1:164
	ds_write2_b32 v198, v76, v77 offset0:48 offset1:180
	ds_write2_b32 v199, v78, v79 offset0:48 offset1:180
	ds_write2_b32 v198, v80, v81 offset0:64 offset1:196
	ds_write2_b32 v199, v82, v83 offset0:64 offset1:196
	ds_write2_b32 v198, v84, v85 offset0:80 offset1:212
	ds_write2_b32 v199, v86, v87 offset0:80 offset1:212
	ds_write2_b32 v198, v88, v89 offset0:96 offset1:228
	ds_write2_b32 v199, v90, v91 offset0:96 offset1:228
	ds_write2_b32 v198, v92, v93 offset0:112 offset1:244
	ds_write2_b32 v199, v94, v95 offset0:112 offset1:244
	v_lshl_add_u64 v[242:243], v[242:243], 0, v[244:245]
	s_waitcnt lgkmcnt(0)
	ds_read_b128 v[64:67], v202
	ds_read_b128 v[68:71], v202 offset:1056
	ds_read_b128 v[72:75], v202 offset:2112
	ds_read_b128 v[76:79], v202 offset:3168
	ds_read_b128 v[80:83], v202 offset:4224
	ds_read_b128 v[84:87], v202 offset:5280
	ds_read_b128 v[88:91], v202 offset:6336
	ds_read_b128 v[92:95], v202 offset:7392
	s_waitcnt lgkmcnt(7)
	v_lshl_add_u64 v[206:207], v[204:205], 0, s[8:9]
	v_cvt_pk_bf16_f32 v64, v64, v65
	v_cvt_pk_bf16_f32 v65, v66, v67
	s_add_u32 s8, s8, s4
	s_addc_u32 s9, s9, 0
	global_store_dwordx2 v[206:207], v[64:65], off
	s_waitcnt lgkmcnt(6)
	v_lshl_add_u64 v[206:207], v[204:205], 0, s[8:9]
	v_cvt_pk_bf16_f32 v68, v68, v69
	v_cvt_pk_bf16_f32 v69, v70, v71
	s_add_u32 s8, s8, s4
	s_addc_u32 s9, s9, 0
	global_store_dwordx2 v[206:207], v[68:69], off
	s_waitcnt lgkmcnt(5)
	v_lshl_add_u64 v[206:207], v[204:205], 0, s[8:9]
	v_cvt_pk_bf16_f32 v72, v72, v73
	v_cvt_pk_bf16_f32 v73, v74, v75
	s_add_u32 s8, s8, s4
	s_addc_u32 s9, s9, 0
	global_store_dwordx2 v[206:207], v[72:73], off
	s_waitcnt lgkmcnt(4)
	v_lshl_add_u64 v[206:207], v[204:205], 0, s[8:9]
	v_cvt_pk_bf16_f32 v76, v76, v77
	v_cvt_pk_bf16_f32 v77, v78, v79
	s_add_u32 s8, s8, s4
	s_addc_u32 s9, s9, 0
	global_store_dwordx2 v[206:207], v[76:77], off
	s_waitcnt lgkmcnt(3)
	v_lshl_add_u64 v[206:207], v[204:205], 0, s[8:9]
	v_cvt_pk_bf16_f32 v80, v80, v81
	v_cvt_pk_bf16_f32 v81, v82, v83
	s_add_u32 s8, s8, s4
	s_addc_u32 s9, s9, 0
	global_store_dwordx2 v[206:207], v[80:81], off
	s_waitcnt lgkmcnt(2)
	v_lshl_add_u64 v[206:207], v[204:205], 0, s[8:9]
	v_cvt_pk_bf16_f32 v84, v84, v85
	v_cvt_pk_bf16_f32 v85, v86, v87
	s_add_u32 s8, s8, s4
	s_addc_u32 s9, s9, 0
	global_store_dwordx2 v[206:207], v[84:85], off
	s_waitcnt lgkmcnt(1)
	v_lshl_add_u64 v[206:207], v[204:205], 0, s[8:9]
	v_cvt_pk_bf16_f32 v88, v88, v89
	v_cvt_pk_bf16_f32 v89, v90, v91
	s_add_u32 s8, s8, s4
	s_addc_u32 s9, s9, 0
	global_store_dwordx2 v[206:207], v[88:89], off
	s_waitcnt lgkmcnt(0)
; DI float shx(float v, int mask, int lane) { return __int_as_float(__builtin_amdgcn_ds_bpermute((lane ^ mask) << 2, __float_as_int(v))); }
; DI void epi_slab(const GemmCfg c, const f32x16 (&acc)[4], float* sW, const float* rss, const size_t row0, const int g, const int lane,
;                  float* const g_h, u16* const g_hb, float* const g_out, const int final_out) {
;     ...
;       } else if (c.epi == EPI_QABS) {
;         f32x4 x = v * rs;
;         float s = x[0] * x[0] + x[1] * x[1] + x[2] * x[2] + x[3] * x[3];
;         s += shx(s, 1, ln_); s += shx(s, 2, ln_); s += shx(s, 4, ln_); s += shx(s, 8, ln_); s += shx(s, 16, ln_);
;         if (l31 == 0) c.f0[row * 32 + g] = s;
;         *(u32x2*)(c.o16 + row * 4096 + col) = MK2(pack2(x[0], x[1]), pack2(x[2], x[3]));
	v_lshl_add_u64 v[206:207], v[204:205], 0, s[8:9]
	v_cvt_pk_bf16_f32 v92, v92, v93
	v_cvt_pk_bf16_f32 v93, v94, v95
	s_add_u32 s8, s8, s4
	s_addc_u32 s9, s9, 0
	global_store_dwordx2 v[206:207], v[92:93], off
	v_pk_mul_f32 v[96:97], v[96:97], v[230:231]
	v_pk_mul_f32 v[98:99], v[98:99], v[232:233]
	v_pk_mul_f32 v[100:101], v[100:101], v[230:231]
	v_pk_mul_f32 v[102:103], v[102:103], v[232:233]
	v_pk_mul_f32 v[104:105], v[104:105], v[230:231]
	v_pk_mul_f32 v[106:107], v[106:107], v[232:233]
	v_pk_mul_f32 v[108:109], v[108:109], v[230:231]
	v_pk_mul_f32 v[110:111], v[110:111], v[232:233]
	v_pk_mul_f32 v[112:113], v[112:113], v[230:231]
	v_pk_mul_f32 v[114:115], v[114:115], v[232:233]
	v_pk_mul_f32 v[116:117], v[116:117], v[230:231]
	v_pk_mul_f32 v[118:119], v[118:119], v[232:233]
	v_pk_mul_f32 v[120:121], v[120:121], v[230:231]
	v_pk_mul_f32 v[122:123], v[122:123], v[232:233]
	v_pk_mul_f32 v[124:125], v[124:125], v[230:231]
	v_pk_mul_f32 v[126:127], v[126:127], v[232:233]
	v_mul_f32_e32 v246, v96, v96
	v_mul_f32_e32 v247, v97, v97
	v_mul_f32_e32 v248, v98, v98
	v_mul_f32_e32 v249, v99, v99
	v_fmac_f32_e32 v246, v100, v100
	v_fmac_f32_e32 v247, v101, v101
	v_fmac_f32_e32 v248, v102, v102
	v_fmac_f32_e32 v249, v103, v103
	v_fmac_f32_e32 v246, v104, v104
	v_fmac_f32_e32 v247, v105, v105
	v_fmac_f32_e32 v248, v106, v106
	v_fmac_f32_e32 v249, v107, v107
	v_fmac_f32_e32 v246, v108, v108
	v_fmac_f32_e32 v247, v109, v109
	v_fmac_f32_e32 v248, v110, v110
	v_fmac_f32_e32 v249, v111, v111
	v_fmac_f32_e32 v246, v112, v112
	v_fmac_f32_e32 v247, v113, v113
	v_fmac_f32_e32 v248, v114, v114
	v_fmac_f32_e32 v249, v115, v115
	v_fmac_f32_e32 v246, v116, v116
	v_fmac_f32_e32 v247, v117, v117
	v_fmac_f32_e32 v248, v118, v118
	v_fmac_f32_e32 v249, v119, v119
	v_fmac_f32_e32 v246, v120, v120
	v_fmac_f32_e32 v247, v121, v121
	v_fmac_f32_e32 v248, v122, v122
	v_fmac_f32_e32 v249, v123, v123
	v_fmac_f32_e32 v246, v124, v124
	v_fmac_f32_e32 v247, v125, v125
	v_fmac_f32_e32 v248, v126, v126
	v_fmac_f32_e32 v249, v127, v127
	v_add_f32_dpp v246, v246, v246 quad_perm:[1,0,3,2] row_mask:0xf bank_mask:0xf
	v_add_f32_dpp v247, v247, v247 quad_perm:[1,0,3,2] row_mask:0xf bank_mask:0xf
	v_add_f32_dpp v248, v248, v248 quad_perm:[1,0,3,2] row_mask:0xf bank_mask:0xf
	v_add_f32_dpp v249, v249, v249 quad_perm:[1,0,3,2] row_mask:0xf bank_mask:0xf
	v_add_f32_dpp v246, v246, v246 quad_perm:[2,3,0,1] row_mask:0xf bank_mask:0xf
	v_add_f32_dpp v247, v247, v247 quad_perm:[2,3,0,1] row_mask:0xf bank_mask:0xf
	v_add_f32_dpp v248, v248, v248 quad_perm:[2,3,0,1] row_mask:0xf bank_mask:0xf
	v_add_f32_dpp v249, v249, v249 quad_perm:[2,3,0,1] row_mask:0xf bank_mask:0xf
	v_add_f32_dpp v246, v246, v246 row_half_mirror row_mask:0xf bank_mask:0xf
	v_add_f32_dpp v247, v247, v247 row_half_mirror row_mask:0xf bank_mask:0xf
	v_add_f32_dpp v248, v248, v248 row_half_mirror row_mask:0xf bank_mask:0xf
	v_add_f32_dpp v249, v249, v249 row_half_mirror row_mask:0xf bank_mask:0xf
	v_add_f32_dpp v246, v246, v246 row_mirror row_mask:0xf bank_mask:0xf
	v_add_f32_dpp v247, v247, v247 row_mirror row_mask:0xf bank_mask:0xf
	v_add_f32_dpp v248, v248, v248 row_mirror row_mask:0xf bank_mask:0xf
	v_add_f32_dpp v249, v249, v249 row_mirror row_mask:0xf bank_mask:0xf
	global_store_dword v[242:243], v246, off offset:0
	global_store_dword v[242:243], v247, off offset:128
	global_store_dword v[242:243], v248, off offset:256
	global_store_dword v[242:243], v249, off offset:384
	ds_write2_b32 v198, v96, v97 offset0:0 offset1:132
	ds_write2_b32 v199, v98, v99 offset0:0 offset1:132
	ds_write2_b32 v198, v100, v101 offset0:16 offset1:148
	ds_write2_b32 v199, v102, v103 offset0:16 offset1:148
	ds_write2_b32 v198, v104, v105 offset0:32 offset1:164
	ds_write2_b32 v199, v106, v107 offset0:32 offset1:164
	ds_write2_b32 v198, v108, v109 offset0:48 offset1:180
	ds_write2_b32 v199, v110, v111 offset0:48 offset1:180
	ds_write2_b32 v198, v112, v113 offset0:64 offset1:196
	ds_write2_b32 v199, v114, v115 offset0:64 offset1:196
	ds_write2_b32 v198, v116, v117 offset0:80 offset1:212
	ds_write2_b32 v199, v118, v119 offset0:80 offset1:212
	ds_write2_b32 v198, v120, v121 offset0:96 offset1:228
	ds_write2_b32 v199, v122, v123 offset0:96 offset1:228
	ds_write2_b32 v198, v124, v125 offset0:112 offset1:244
	ds_write2_b32 v199, v126, v127 offset0:112 offset1:244
	v_lshl_add_u64 v[242:243], v[242:243], 0, v[244:245]
	s_waitcnt lgkmcnt(0)
	ds_read_b128 v[96:99], v202
	ds_read_b128 v[100:103], v202 offset:1056
	ds_read_b128 v[104:107], v202 offset:2112
	ds_read_b128 v[108:111], v202 offset:3168
	ds_read_b128 v[112:115], v202 offset:4224
	ds_read_b128 v[116:119], v202 offset:5280
	ds_read_b128 v[120:123], v202 offset:6336
	ds_read_b128 v[124:127], v202 offset:7392
	s_waitcnt lgkmcnt(7)
	v_lshl_add_u64 v[206:207], v[204:205], 0, s[8:9]
	v_cvt_pk_bf16_f32 v96, v96, v97
	v_cvt_pk_bf16_f32 v97, v98, v99
	s_add_u32 s8, s8, s4
	s_addc_u32 s9, s9, 0
	global_store_dwordx2 v[206:207], v[96:97], off
	s_waitcnt lgkmcnt(6)
	v_lshl_add_u64 v[206:207], v[204:205], 0, s[8:9]
	v_cvt_pk_bf16_f32 v100, v100, v101
	v_cvt_pk_bf16_f32 v101, v102, v103
	s_add_u32 s8, s8, s4
	s_addc_u32 s9, s9, 0
	global_store_dwordx2 v[206:207], v[100:101], off
	s_waitcnt lgkmcnt(5)
	v_lshl_add_u64 v[206:207], v[204:205], 0, s[8:9]
	v_cvt_pk_bf16_f32 v104, v104, v105
	v_cvt_pk_bf16_f32 v105, v106, v107
	s_add_u32 s8, s8, s4
	s_addc_u32 s9, s9, 0
	global_store_dwordx2 v[206:207], v[104:105], off
	s_waitcnt lgkmcnt(4)
	v_lshl_add_u64 v[206:207], v[204:205], 0, s[8:9]
	v_cvt_pk_bf16_f32 v108, v108, v109
	v_cvt_pk_bf16_f32 v109, v110, v111
	s_add_u32 s8, s8, s4
	s_addc_u32 s9, s9, 0
	global_store_dwordx2 v[206:207], v[108:109], off
	s_waitcnt lgkmcnt(3)
; DI float shx(float v, int mask, int lane) { return __int_as_float(__builtin_amdgcn_ds_bpermute((lane ^ mask) << 2, __float_as_int(v))); }
; DI void epi_slab(const GemmCfg c, const f32x16 (&acc)[4], float* sW, const float* rss, const size_t row0, const int g, const int lane,
;                  float* const g_h, u16* const g_hb, float* const g_out, const int final_out) {
;     ...
;       } else if (c.epi == EPI_QABS) {
;         f32x4 x = v * rs;
;         float s = x[0] * x[0] + x[1] * x[1] + x[2] * x[2] + x[3] * x[3];
;         s += shx(s, 1, ln_); s += shx(s, 2, ln_); s += shx(s, 4, ln_); s += shx(s, 8, ln_); s += shx(s, 16, ln_);
;         if (l31 == 0) c.f0[row * 32 + g] = s;
;         *(u32x2*)(c.o16 + row * 4096 + col) = MK2(pack2(x[0], x[1]), pack2(x[2], x[3]));
	v_lshl_add_u64 v[206:207], v[204:205], 0, s[8:9]
	v_cvt_pk_bf16_f32 v112, v112, v113
	v_cvt_pk_bf16_f32 v113, v114, v115
	s_add_u32 s8, s8, s4
	s_addc_u32 s9, s9, 0
	global_store_dwordx2 v[206:207], v[112:113], off
	s_waitcnt lgkmcnt(2)
	v_lshl_add_u64 v[206:207], v[204:205], 0, s[8:9]
	v_cvt_pk_bf16_f32 v116, v116, v117
	v_cvt_pk_bf16_f32 v117, v118, v119
	s_add_u32 s8, s8, s4
	s_addc_u32 s9, s9, 0
	global_store_dwordx2 v[206:207], v[116:117], off
	s_waitcnt lgkmcnt(1)
	v_lshl_add_u64 v[206:207], v[204:205], 0, s[8:9]
	v_cvt_pk_bf16_f32 v120, v120, v121
	v_cvt_pk_bf16_f32 v121, v122, v123
	s_add_u32 s8, s8, s4
	s_addc_u32 s9, s9, 0
	global_store_dwordx2 v[206:207], v[120:121], off
	s_waitcnt lgkmcnt(0)
	v_lshl_add_u64 v[206:207], v[204:205], 0, s[8:9]
	v_cvt_pk_bf16_f32 v124, v124, v125
	v_cvt_pk_bf16_f32 v125, v126, v127
	s_add_u32 s8, s8, s4
	s_addc_u32 s9, s9, 0
	global_store_dwordx2 v[206:207], v[124:125], off
	v_pk_mul_f32 v[0:1], v[0:1], v[234:235]
	v_pk_mul_f32 v[2:3], v[2:3], v[236:237]
	v_pk_mul_f32 v[4:5], v[4:5], v[234:235]
	v_pk_mul_f32 v[6:7], v[6:7], v[236:237]
	v_pk_mul_f32 v[8:9], v[8:9], v[234:235]
	v_pk_mul_f32 v[10:11], v[10:11], v[236:237]
	v_pk_mul_f32 v[12:13], v[12:13], v[234:235]
	v_pk_mul_f32 v[14:15], v[14:15], v[236:237]
	v_pk_mul_f32 v[16:17], v[16:17], v[234:235]
	v_pk_mul_f32 v[18:19], v[18:19], v[236:237]
	v_pk_mul_f32 v[20:21], v[20:21], v[234:235]
	v_pk_mul_f32 v[22:23], v[22:23], v[236:237]
	v_pk_mul_f32 v[24:25], v[24:25], v[234:235]
	v_pk_mul_f32 v[26:27], v[26:27], v[236:237]
	v_pk_mul_f32 v[28:29], v[28:29], v[234:235]
	v_pk_mul_f32 v[30:31], v[30:31], v[236:237]
	v_mul_f32_e32 v246, v0, v0
	v_mul_f32_e32 v247, v1, v1
	v_mul_f32_e32 v248, v2, v2
	v_mul_f32_e32 v249, v3, v3
	v_fmac_f32_e32 v246, v4, v4
	v_fmac_f32_e32 v247, v5, v5
	v_fmac_f32_e32 v248, v6, v6
	v_fmac_f32_e32 v249, v7, v7
	v_fmac_f32_e32 v246, v8, v8
	v_fmac_f32_e32 v247, v9, v9
	v_fmac_f32_e32 v248, v10, v10
	v_fmac_f32_e32 v249, v11, v11
	v_fmac_f32_e32 v246, v12, v12
	v_fmac_f32_e32 v247, v13, v13
	v_fmac_f32_e32 v248, v14, v14
	v_fmac_f32_e32 v249, v15, v15
	v_fmac_f32_e32 v246, v16, v16
	v_fmac_f32_e32 v247, v17, v17
	v_fmac_f32_e32 v248, v18, v18
	v_fmac_f32_e32 v249, v19, v19
	v_fmac_f32_e32 v246, v20, v20
	v_fmac_f32_e32 v247, v21, v21
	v_fmac_f32_e32 v248, v22, v22
	v_fmac_f32_e32 v249, v23, v23
	v_fmac_f32_e32 v246, v24, v24
	v_fmac_f32_e32 v247, v25, v25
	v_fmac_f32_e32 v248, v26, v26
	v_fmac_f32_e32 v249, v27, v27
	v_fmac_f32_e32 v246, v28, v28
	v_fmac_f32_e32 v247, v29, v29
	v_fmac_f32_e32 v248, v30, v30
	v_fmac_f32_e32 v249, v31, v31
	v_add_f32_dpp v246, v246, v246 quad_perm:[1,0,3,2] row_mask:0xf bank_mask:0xf
	v_add_f32_dpp v247, v247, v247 quad_perm:[1,0,3,2] row_mask:0xf bank_mask:0xf
	v_add_f32_dpp v248, v248, v248 quad_perm:[1,0,3,2] row_mask:0xf bank_mask:0xf
	v_add_f32_dpp v249, v249, v249 quad_perm:[1,0,3,2] row_mask:0xf bank_mask:0xf
	v_add_f32_dpp v246, v246, v246 quad_perm:[2,3,0,1] row_mask:0xf bank_mask:0xf
	v_add_f32_dpp v247, v247, v247 quad_perm:[2,3,0,1] row_mask:0xf bank_mask:0xf
	v_add_f32_dpp v248, v248, v248 quad_perm:[2,3,0,1] row_mask:0xf bank_mask:0xf
	v_add_f32_dpp v249, v249, v249 quad_perm:[2,3,0,1] row_mask:0xf bank_mask:0xf
	v_add_f32_dpp v246, v246, v246 row_half_mirror row_mask:0xf bank_mask:0xf
	v_add_f32_dpp v247, v247, v247 row_half_mirror row_mask:0xf bank_mask:0xf
	v_add_f32_dpp v248, v248, v248 row_half_mirror row_mask:0xf bank_mask:0xf
	v_add_f32_dpp v249, v249, v249 row_half_mirror row_mask:0xf bank_mask:0xf
	v_add_f32_dpp v246, v246, v246 row_mirror row_mask:0xf bank_mask:0xf
	v_add_f32_dpp v247, v247, v247 row_mirror row_mask:0xf bank_mask:0xf
	v_add_f32_dpp v248, v248, v248 row_mirror row_mask:0xf bank_mask:0xf
	v_add_f32_dpp v249, v249, v249 row_mirror row_mask:0xf bank_mask:0xf
	global_store_dword v[242:243], v246, off offset:0
	global_store_dword v[242:243], v247, off offset:128
	global_store_dword v[242:243], v248, off offset:256
	global_store_dword v[242:243], v249, off offset:384
	ds_write2_b32 v198, v0, v1 offset0:0 offset1:132
	ds_write2_b32 v199, v2, v3 offset0:0 offset1:132
	ds_write2_b32 v198, v4, v5 offset0:16 offset1:148
	ds_write2_b32 v199, v6, v7 offset0:16 offset1:148
	ds_write2_b32 v198, v8, v9 offset0:32 offset1:164
	ds_write2_b32 v199, v10, v11 offset0:32 offset1:164
	ds_write2_b32 v198, v12, v13 offset0:48 offset1:180
	ds_write2_b32 v199, v14, v15 offset0:48 offset1:180
	ds_write2_b32 v198, v16, v17 offset0:64 offset1:196
	ds_write2_b32 v199, v18, v19 offset0:64 offset1:196
	ds_write2_b32 v198, v20, v21 offset0:80 offset1:212
	ds_write2_b32 v199, v22, v23 offset0:80 offset1:212
	ds_write2_b32 v198, v24, v25 offset0:96 offset1:228
	ds_write2_b32 v199, v26, v27 offset0:96 offset1:228
	ds_write2_b32 v198, v28, v29 offset0:112 offset1:244
	ds_write2_b32 v199, v30, v31 offset0:112 offset1:244
	v_lshl_add_u64 v[242:243], v[242:243], 0, v[244:245]
	s_waitcnt lgkmcnt(0)
	ds_read_b128 v[0:3], v202
	ds_read_b128 v[4:7], v202 offset:1056
	ds_read_b128 v[8:11], v202 offset:2112
	ds_read_b128 v[12:15], v202 offset:3168
	ds_read_b128 v[16:19], v202 offset:4224
	ds_read_b128 v[20:23], v202 offset:5280
	ds_read_b128 v[24:27], v202 offset:6336
	ds_read_b128 v[28:31], v202 offset:7392
	s_waitcnt lgkmcnt(7)
	v_lshl_add_u64 v[206:207], v[204:205], 0, s[8:9]
	v_cvt_pk_bf16_f32 v0, v0, v1
	v_cvt_pk_bf16_f32 v1, v2, v3
	s_add_u32 s8, s8, s4
	s_addc_u32 s9, s9, 0
	global_store_dwordx2 v[206:207], v[0:1], off
	s_waitcnt lgkmcnt(6)
	v_lshl_add_u64 v[206:207], v[204:205], 0, s[8:9]
	v_cvt_pk_bf16_f32 v4, v4, v5
	v_cvt_pk_bf16_f32 v5, v6, v7
	s_add_u32 s8, s8, s4
	s_addc_u32 s9, s9, 0
	global_store_dwordx2 v[206:207], v[4:5], off
	s_waitcnt lgkmcnt(5)
; DI float shx(float v, int mask, int lane) { return __int_as_float(__builtin_amdgcn_ds_bpermute((lane ^ mask) << 2, __float_as_int(v))); }
; DI void epi_slab(const GemmCfg c, const f32x16 (&acc)[4], float* sW, const float* rss, const size_t row0, const int g, const int lane,
;                  float* const g_h, u16* const g_hb, float* const g_out, const int final_out) {
;     ...
;       } else if (c.epi == EPI_QABS) {
;         f32x4 x = v * rs;
;         float s = x[0] * x[0] + x[1] * x[1] + x[2] * x[2] + x[3] * x[3];
;         s += shx(s, 1, ln_); s += shx(s, 2, ln_); s += shx(s, 4, ln_); s += shx(s, 8, ln_); s += shx(s, 16, ln_);
;         if (l31 == 0) c.f0[row * 32 + g] = s;
;         *(u32x2*)(c.o16 + row * 4096 + col) = MK2(pack2(x[0], x[1]), pack2(x[2], x[3]));
	v_lshl_add_u64 v[206:207], v[204:205], 0, s[8:9]
	v_cvt_pk_bf16_f32 v8, v8, v9
	v_cvt_pk_bf16_f32 v9, v10, v11
	s_add_u32 s8, s8, s4
	s_addc_u32 s9, s9, 0
	global_store_dwordx2 v[206:207], v[8:9], off
	s_waitcnt lgkmcnt(4)
	v_lshl_add_u64 v[206:207], v[204:205], 0, s[8:9]
	v_cvt_pk_bf16_f32 v12, v12, v13
	v_cvt_pk_bf16_f32 v13, v14, v15
	s_add_u32 s8, s8, s4
	s_addc_u32 s9, s9, 0
	global_store_dwordx2 v[206:207], v[12:13], off
	s_waitcnt lgkmcnt(3)
	v_lshl_add_u64 v[206:207], v[204:205], 0, s[8:9]
	v_cvt_pk_bf16_f32 v16, v16, v17
	v_cvt_pk_bf16_f32 v17, v18, v19
	s_add_u32 s8, s8, s4
	s_addc_u32 s9, s9, 0
	global_store_dwordx2 v[206:207], v[16:17], off
	s_waitcnt lgkmcnt(2)
	v_lshl_add_u64 v[206:207], v[204:205], 0, s[8:9]
	v_cvt_pk_bf16_f32 v20, v20, v21
	v_cvt_pk_bf16_f32 v21, v22, v23
	s_add_u32 s8, s8, s4
	s_addc_u32 s9, s9, 0
	global_store_dwordx2 v[206:207], v[20:21], off
	s_waitcnt lgkmcnt(1)
	v_lshl_add_u64 v[206:207], v[204:205], 0, s[8:9]
	v_cvt_pk_bf16_f32 v24, v24, v25
	v_cvt_pk_bf16_f32 v25, v26, v27
	s_add_u32 s8, s8, s4
	s_addc_u32 s9, s9, 0
	global_store_dwordx2 v[206:207], v[24:25], off
	s_waitcnt lgkmcnt(0)
	v_lshl_add_u64 v[206:207], v[204:205], 0, s[8:9]
	v_cvt_pk_bf16_f32 v28, v28, v29
	v_cvt_pk_bf16_f32 v29, v30, v31
	s_add_u32 s8, s8, s4
	s_addc_u32 s9, s9, 0
	global_store_dwordx2 v[206:207], v[28:29], off
	v_pk_mul_f32 v[32:33], v[32:33], v[238:239]
	v_pk_mul_f32 v[34:35], v[34:35], v[240:241]
	v_pk_mul_f32 v[36:37], v[36:37], v[238:239]
	v_pk_mul_f32 v[38:39], v[38:39], v[240:241]
	v_pk_mul_f32 v[40:41], v[40:41], v[238:239]
	v_pk_mul_f32 v[42:43], v[42:43], v[240:241]
	v_pk_mul_f32 v[44:45], v[44:45], v[238:239]
	v_pk_mul_f32 v[46:47], v[46:47], v[240:241]
	v_pk_mul_f32 v[48:49], v[48:49], v[238:239]
	v_pk_mul_f32 v[50:51], v[50:51], v[240:241]
	v_pk_mul_f32 v[52:53], v[52:53], v[238:239]
	v_pk_mul_f32 v[54:55], v[54:55], v[240:241]
	v_pk_mul_f32 v[56:57], v[56:57], v[238:239]
	v_pk_mul_f32 v[58:59], v[58:59], v[240:241]
	v_pk_mul_f32 v[60:61], v[60:61], v[238:239]
	v_pk_mul_f32 v[62:63], v[62:63], v[240:241]
	v_mul_f32_e32 v246, v32, v32
	v_mul_f32_e32 v247, v33, v33
	v_mul_f32_e32 v248, v34, v34
	v_mul_f32_e32 v249, v35, v35
	v_fmac_f32_e32 v246, v36, v36
	v_fmac_f32_e32 v247, v37, v37
	v_fmac_f32_e32 v248, v38, v38
	v_fmac_f32_e32 v249, v39, v39
	v_fmac_f32_e32 v246, v40, v40
	v_fmac_f32_e32 v247, v41, v41
	v_fmac_f32_e32 v248, v42, v42
	v_fmac_f32_e32 v249, v43, v43
	v_fmac_f32_e32 v246, v44, v44
	v_fmac_f32_e32 v247, v45, v45
	v_fmac_f32_e32 v248, v46, v46
	v_fmac_f32_e32 v249, v47, v47
	v_fmac_f32_e32 v246, v48, v48
	v_fmac_f32_e32 v247, v49, v49
	v_fmac_f32_e32 v248, v50, v50
	v_fmac_f32_e32 v249, v51, v51
	v_fmac_f32_e32 v246, v52, v52
	v_fmac_f32_e32 v247, v53, v53
	v_fmac_f32_e32 v248, v54, v54
	v_fmac_f32_e32 v249, v55, v55
	v_fmac_f32_e32 v246, v56, v56
	v_fmac_f32_e32 v247, v57, v57
	v_fmac_f32_e32 v248, v58, v58
	v_fmac_f32_e32 v249, v59, v59
	v_fmac_f32_e32 v246, v60, v60
	v_fmac_f32_e32 v247, v61, v61
	v_fmac_f32_e32 v248, v62, v62
	v_fmac_f32_e32 v249, v63, v63
	v_add_f32_dpp v246, v246, v246 quad_perm:[1,0,3,2] row_mask:0xf bank_mask:0xf
	v_add_f32_dpp v247, v247, v247 quad_perm:[1,0,3,2] row_mask:0xf bank_mask:0xf
	v_add_f32_dpp v248, v248, v248 quad_perm:[1,0,3,2] row_mask:0xf bank_mask:0xf
	v_add_f32_dpp v249, v249, v249 quad_perm:[1,0,3,2] row_mask:0xf bank_mask:0xf
	v_add_f32_dpp v246, v246, v246 quad_perm:[2,3,0,1] row_mask:0xf bank_mask:0xf
	v_add_f32_dpp v247, v247, v247 quad_perm:[2,3,0,1] row_mask:0xf bank_mask:0xf
	v_add_f32_dpp v248, v248, v248 quad_perm:[2,3,0,1] row_mask:0xf bank_mask:0xf
	v_add_f32_dpp v249, v249, v249 quad_perm:[2,3,0,1] row_mask:0xf bank_mask:0xf
	v_add_f32_dpp v246, v246, v246 row_half_mirror row_mask:0xf bank_mask:0xf
	v_add_f32_dpp v247, v247, v247 row_half_mirror row_mask:0xf bank_mask:0xf
	v_add_f32_dpp v248, v248, v248 row_half_mirror row_mask:0xf bank_mask:0xf
	v_add_f32_dpp v249, v249, v249 row_half_mirror row_mask:0xf bank_mask:0xf
	v_add_f32_dpp v246, v246, v246 row_mirror row_mask:0xf bank_mask:0xf
	v_add_f32_dpp v247, v247, v247 row_mirror row_mask:0xf bank_mask:0xf
	v_add_f32_dpp v248, v248, v248 row_mirror row_mask:0xf bank_mask:0xf
	v_add_f32_dpp v249, v249, v249 row_mirror row_mask:0xf bank_mask:0xf
	global_store_dword v[242:243], v246, off offset:0
	global_store_dword v[242:243], v247, off offset:128
	global_store_dword v[242:243], v248, off offset:256
	global_store_dword v[242:243], v249, off offset:384
	ds_write2_b32 v198, v32, v33 offset0:0 offset1:132
	ds_write2_b32 v199, v34, v35 offset0:0 offset1:132
	ds_write2_b32 v198, v36, v37 offset0:16 offset1:148
	ds_write2_b32 v199, v38, v39 offset0:16 offset1:148
	ds_write2_b32 v198, v40, v41 offset0:32 offset1:164
	ds_write2_b32 v199, v42, v43 offset0:32 offset1:164
	ds_write2_b32 v198, v44, v45 offset0:48 offset1:180
	ds_write2_b32 v199, v46, v47 offset0:48 offset1:180
	ds_write2_b32 v198, v48, v49 offset0:64 offset1:196
	ds_write2_b32 v199, v50, v51 offset0:64 offset1:196
	ds_write2_b32 v198, v52, v53 offset0:80 offset1:212
	ds_write2_b32 v199, v54, v55 offset0:80 offset1:212
	ds_write2_b32 v198, v56, v57 offset0:96 offset1:228
	ds_write2_b32 v199, v58, v59 offset0:96 offset1:228
	ds_write2_b32 v198, v60, v61 offset0:112 offset1:244
	ds_write2_b32 v199, v62, v63 offset0:112 offset1:244
	s_waitcnt lgkmcnt(0)
; DI float shx(float v, int mask, int lane) { return __int_as_float(__builtin_amdgcn_ds_bpermute((lane ^ mask) << 2, __float_as_int(v))); }
; DI void epi_slab(const GemmCfg c, const f32x16 (&acc)[4], float* sW, const float* rss, const size_t row0, const int g, const int lane,
;                  float* const g_h, u16* const g_hb, float* const g_out, const int final_out) {
;     ...
;       } else if (c.epi == EPI_QABS) {
;         f32x4 x = v * rs;
;         float s = x[0] * x[0] + x[1] * x[1] + x[2] * x[2] + x[3] * x[3];
;         s += shx(s, 1, ln_); s += shx(s, 2, ln_); s += shx(s, 4, ln_); s += shx(s, 8, ln_); s += shx(s, 16, ln_);
;         if (l31 == 0) c.f0[row * 32 + g] = s;
;         *(u32x2*)(c.o16 + row * 4096 + col) = MK2(pack2(x[0], x[1]), pack2(x[2], x[3]));
	ds_read_b128 v[32:35], v202
	ds_read_b128 v[36:39], v202 offset:1056
	ds_read_b128 v[40:43], v202 offset:2112
	ds_read_b128 v[44:47], v202 offset:3168
	ds_read_b128 v[48:51], v202 offset:4224
	ds_read_b128 v[52:55], v202 offset:5280
	ds_read_b128 v[56:59], v202 offset:6336
	ds_read_b128 v[60:63], v202 offset:7392
	s_waitcnt lgkmcnt(7)
	v_lshl_add_u64 v[206:207], v[204:205], 0, s[8:9]
	v_cvt_pk_bf16_f32 v32, v32, v33
	v_cvt_pk_bf16_f32 v33, v34, v35
	s_add_u32 s8, s8, s4
	s_addc_u32 s9, s9, 0
	global_store_dwordx2 v[206:207], v[32:33], off
	s_waitcnt lgkmcnt(6)
	v_lshl_add_u64 v[206:207], v[204:205], 0, s[8:9]
	v_cvt_pk_bf16_f32 v36, v36, v37
	v_cvt_pk_bf16_f32 v37, v38, v39
	s_add_u32 s8, s8, s4
	s_addc_u32 s9, s9, 0
	global_store_dwordx2 v[206:207], v[36:37], off
	s_waitcnt lgkmcnt(5)
	v_lshl_add_u64 v[206:207], v[204:205], 0, s[8:9]
	v_cvt_pk_bf16_f32 v40, v40, v41
	v_cvt_pk_bf16_f32 v41, v42, v43
	s_add_u32 s8, s8, s4
	s_addc_u32 s9, s9, 0
	global_store_dwordx2 v[206:207], v[40:41], off
	s_waitcnt lgkmcnt(4)
	v_lshl_add_u64 v[206:207], v[204:205], 0, s[8:9]
	v_cvt_pk_bf16_f32 v44, v44, v45
	v_cvt_pk_bf16_f32 v45, v46, v47
	s_add_u32 s8, s8, s4
	s_addc_u32 s9, s9, 0
	global_store_dwordx2 v[206:207], v[44:45], off
	s_waitcnt lgkmcnt(3)
	v_lshl_add_u64 v[206:207], v[204:205], 0, s[8:9]
	v_cvt_pk_bf16_f32 v48, v48, v49
	v_cvt_pk_bf16_f32 v49, v50, v51
	s_add_u32 s8, s8, s4
	s_addc_u32 s9, s9, 0
	global_store_dwordx2 v[206:207], v[48:49], off
	s_waitcnt lgkmcnt(2)
	v_lshl_add_u64 v[206:207], v[204:205], 0, s[8:9]
	v_cvt_pk_bf16_f32 v52, v52, v53
	v_cvt_pk_bf16_f32 v53, v54, v55
	s_add_u32 s8, s8, s4
	s_addc_u32 s9, s9, 0
	global_store_dwordx2 v[206:207], v[52:53], off
	s_waitcnt lgkmcnt(1)
	v_lshl_add_u64 v[206:207], v[204:205], 0, s[8:9]
	v_cvt_pk_bf16_f32 v56, v56, v57
	v_cvt_pk_bf16_f32 v57, v58, v59
	s_add_u32 s8, s8, s4
	s_addc_u32 s9, s9, 0
	global_store_dwordx2 v[206:207], v[56:57], off
	s_waitcnt lgkmcnt(0)
	v_lshl_add_u64 v[206:207], v[204:205], 0, s[8:9]
	v_cvt_pk_bf16_f32 v60, v60, v61
	v_cvt_pk_bf16_f32 v61, v62, v63
	s_add_u32 s8, s8, s4
	s_addc_u32 s9, s9, 0
	global_store_dwordx2 v[206:207], v[60:61], off
	s_branch .LBB0_108
